# norm: next-row loads after shift/scale loads; ret_out: scalar logit loads (prefetch no longer drained), q loads before first barrier
# speedup vs baseline: 1.0529x; 1.0009x over previous
; #define LAS __attribute__((address_space(3)))
; __device__ __forceinline__ void ret_prefetch(const Frame& F, int it, int nchu, RetPre& P) {
;     const int bh = it / nchu, mc = it - bh * nchu + (NCH - nchu), h = bh & 7, b = bh >> 3;
;     const int tid = F.tid;
;     const size_t rowbase = (size_t)b * TB + 128 * mc;
; #pragma unroll
;     for (int i = 0; i < 2; ++i) {
;         const int u = tid + i * NTHREADS, r = u >> 3, c8 = (u & 7) * 8;
;         P.k[i] = *(const u32x4*)(WSB(WS_KN) + (rowbase + r) * 512 + h * 64 + c8);
;         P.sf[i] = *(const u32x4*)(WSB(WS_ST) + ((((size_t)(b * NH + h) * 2 + 0) * NCH + mc) * DV + r) * DK + c8);
;         P.sb[i] = *(const u32x4*)(WSB(WS_ST) + ((((size_t)(b * NH + h) * 2 + 1) * NCH + mc) * DV + r) * DK + c8);
;     }
; #pragma unroll
;     for (int i = 0; i < 4; ++i) {
;         const int u = tid + i * NTHREADS, r = u >> 4, c8 = (u & 15) * 8;
;         P.vt[i] = *(const u32x4*)(WSB(WS_VT) + ((size_t)(b * NH + h) * DV + r) * TB + 128 * mc + c8);
;     }
; __device__ __forceinline__ void ret_out_phase(const Args& A, Frame& F, int l, bool lastl, bf16_t* ARET, bf16_t* ALRU) {
;     ...
;     for (int jx = 0; jx < nmy; ++jx) {
;         const int it = F.bid + jx * F.G, itn = (jx + 1 < nmy) ? it + F.G : it;
;         const int bh = it / NCHU, mc = it - bh * NCHU + (NCH - NCHU), h = bh & 7, b = bh >> 3;
;         const size_t rowbase = (size_t)b * TB + 128 * mc;
;         __syncthreads();
; #pragma unroll
;         for (int i = 0; i < 2; ++i) {
;             const int u = tid + i * NTHREADS, r = u >> 3, c8 = (u & 7) * 8;
;             *(LAS u32x4*)(ks_ + r * 72 + c8) = P.k[i]; *(LAS u32x4*)(sfs + r * 72 + c8) = P.sf[i]; *(LAS u32x4*)(sbs + r * 72 + c8) = P.sb[i];
;         }
; #pragma unroll
;         for (int i = 0; i < 4; ++i) { const int u = tid + i * NTHREADS, r = u >> 4, c8 = (u & 15) * 8; *(LAS u32x4*)(vts + r * 136 + c8) = P.vt[i]; }
;         bf16x8 qf[2];
; #pragma unroll
;         for (int ks = 0; ks < 2; ++ks) qf[ks] = *(const bf16x8*)(WSB(WS_Q) + (rowbase + 16 * w + fr) * 512 + h * 64 + 32 * ks + 8 * fq);
;         __syncthreads();
;         ret_prefetch(F, itn, NCHU, P);
;         const float l2f = log2_gamma(A, F, l, 0, h), l2b = log2_gamma(A, F, l, 1, h);
.LBB0_30:
	s_add_i32 s39, s39, 1
	s_cmp_lt_i32 s39, s37
	s_cselect_b32 s2, s34, 0
	s_abs_i32 s5, vcc_hi
	s_mul_hi_u32 s8, s5, s45
	s_mul_i32 s9, s8, s20
	s_sub_i32 s5, s5, s9
	s_ashr_i32 s4, vcc_hi, 31
	s_add_i32 s9, s8, 1
	s_sub_i32 s25, s5, s20
	s_cmp_ge_u32 s5, s20
	s_cselect_b32 s8, s9, s8
	s_cselect_b32 s5, s25, s5
	s_add_i32 s9, s8, 1
	s_cmp_ge_u32 s5, s20
	s_cselect_b32 s5, s9, s8
	s_xor_b32 s5, s5, s4
	s_sub_i32 s4, s5, s4
	s_not_b32 s5, s4
	s_mul_i32 s5, vcc_lo, s5
	s_ashr_i32 s8, s4, 3
	s_add_i32 s5, s61, s5
	s_ashr_i32 s9, s5, 31
	s_add_i32 s25, s2, vcc_hi
	s_mul_hi_i32 s52, s8, 0x900
	s_mulk_i32 s8, 0x900
	s_and_b32 s2, s4, 7
	s_add_u32 s8, s8, s5
	s_addc_u32 s9, s52, s9
	s_abs_i32 s5, s25
	s_mul_hi_u32 s52, s5, s45
	s_mul_i32 s53, s52, s20
	s_sub_i32 s5, s5, s53
	s_lshl_b32 s82, s2, 7
	s_ashr_i32 s4, s25, 31
	s_add_i32 s53, s52, 1
	s_sub_i32 s58, s5, s20
	s_cmp_ge_u32 s5, s20
	s_cselect_b32 s52, s53, s52
	s_cselect_b32 s5, s58, s5
	s_add_i32 s53, s52, 1
	s_cmp_ge_u32 s5, s20
	s_cselect_b32 s5, s53, s52
	s_xor_b32 s5, s5, s4
	s_sub_i32 s4, s5, s4
	s_not_b32 s5, s4
	s_mul_i32 s5, s20, s5
	s_add_i32 s5, s25, s5
	v_lshl_add_u64 v[50:51], v[122:123], 0, s[8:9]
	v_lshlrev_b64 v[50:51], 10, v[50:51]
	v_lshl_add_u64 v[50:51], s[48:49], 0, v[50:51]
	v_lshl_add_u64 v[50:51], v[50:51], 0, s[82:83]
	v_lshl_add_u64 v[50:51], v[50:51], 0, v[0:1]
	global_load_dwordx4 v[46:49], v[50:51], off
	global_load_dwordx4 v[42:45], v[50:51], off offset:64
	s_barrier
	s_waitcnt vmcnt(0)
	ds_write_b128 v134, v[6:9]
	ds_write_b128 v134, v[10:13] offset:53248
	ds_write_b128 v135, v[2:5]
	ds_write_b128 v136, v[22:25]
	ds_write_b128 v136, v[26:29] offset:53248
	ds_write_b128 v137, v[34:37]
	v_lshl_add_u64 v[2:3], v[122:123], 0, s[8:9]
	s_add_i32 s25, s5, 18
	v_lshlrev_b64 v[2:3], 10, v[2:3]
	s_ashr_i32 s5, s4, 3
	s_lshl_b32 s72, s25, 7
	v_lshl_add_u64 v[2:3], s[48:49], 0, v[2:3]
	s_mul_hi_i32 s52, s5, 0x900
	s_mulk_i32 s5, 0x900
	s_ashr_i32 s73, s72, 31
	v_lshl_add_u64 v[2:3], v[2:3], 0, s[82:83]
	s_add_u32 s92, s5, s72
	ds_write_b128 v245, v[14:17] offset:18432
	ds_write_b128 v246, v[18:21] offset:18432
	ds_write_b128 v247, v[30:33] offset:18432
	ds_write_b128 v248, v[38:41] offset:18432
	v_lshl_add_u64 v[2:3], v[2:3], 0, v[0:1]
	s_addc_u32 s93, s52, s73
	s_ashr_i32 s5, s4, 31
	s_mul_i32 s52, s4, 36
	s_ashr_i32 s58, s25, 31
	s_mul_hi_i32 s53, s4, 36
	s_add_u32 s52, s52, s25
	v_lshl_add_u64 v[2:3], s[92:93], 0, v[116:117]
	v_lshl_add_u64 v[14:15], s[92:93], 0, v[114:115]
	s_addc_u32 s53, s53, s58
	v_lshlrev_b64 v[2:3], 10, v[2:3]
	s_lshl_b32 s25, s4, 7
	v_lshlrev_b64 v[14:15], 10, v[14:15]
	s_lshl_b64 s[52:53], s[52:53], 14
	v_lshl_add_u64 v[2:3], s[6:7], 0, v[2:3]
	s_and_b32 s78, s25, 0x380
	s_mov_b32 s79, s83
	v_lshl_add_u64 v[14:15], s[6:7], 0, v[14:15]
	v_lshl_add_u64 v[2:3], v[2:3], 0, s[78:79]
	v_mov_b32_e32 v129, v1
	s_add_u32 s76, s62, s52
	v_lshl_add_u64 v[14:15], v[14:15], 0, s[78:79]
	v_lshl_add_u64 v[2:3], v[2:3], 0, v[128:129]
	s_addc_u32 s77, s63, s53
	v_lshl_add_u64 v[14:15], v[14:15], 0, v[128:129]
	s_waitcnt lgkmcnt(0)
	s_barrier
	global_load_dwordx4 v[6:9], v[2:3], off
	global_load_dwordx4 v[22:25], v[14:15], off
	v_lshl_add_u64 v[2:3], s[76:77], 0, v[120:121]
	s_add_u32 s74, s65, s52
	v_lshl_add_u64 v[14:15], s[76:77], 0, v[118:119]
	v_lshl_add_u64 v[2:3], v[2:3], 0, v[128:129]
	s_addc_u32 s75, s19, s53
	v_lshl_add_u64 v[14:15], v[14:15], 0, v[128:129]
	global_load_dwordx4 v[10:13], v[2:3], off
	global_load_dwordx4 v[26:29], v[14:15], off
	v_lshl_add_u64 v[2:3], s[74:75], 0, v[120:121]
	v_lshl_add_u64 v[14:15], s[74:75], 0, v[118:119]
	v_lshl_add_u64 v[2:3], v[2:3], 0, v[128:129]
	v_lshl_add_u64 v[14:15], v[14:15], 0, v[128:129]
	s_lshl_b64 s[74:75], s[4:5], 7
	global_load_dwordx4 v[2:5], v[2:3], off
	v_mov_b64_e32 v[38:39], s[54:55]
	global_load_dwordx4 v[34:37], v[14:15], off
	v_lshl_add_u64 v[14:15], s[74:75], 0, v[106:107]
	v_lshl_add_u64 v[18:19], s[74:75], 0, v[108:109]
	v_lshl_add_u64 v[30:31], s[74:75], 0, v[110:111]
	v_lshl_add_u64 v[50:51], s[74:75], 0, v[112:113]
	v_mad_u64_u32 v[16:17], s[4:5], v14, s96, v[38:39]
	v_mad_u64_u32 v[20:21], s[52:53], v18, s96, v[38:39]
	v_mad_u64_u32 v[32:33], s[52:53], v30, s96, v[38:39]
	v_mad_u64_u32 v[38:39], s[52:53], v50, s96, v[38:39]
	s_load_dwordx2 s[74:75], s[46:47], 0x60
	v_mad_i32_i24 v17, v15, s96, v17
	s_lshl_b64 s[4:5], s[72:73], 1
	v_mad_i32_i24 v21, v19, s96, v21
	v_mad_i32_i24 v33, v31, s96, v33
	v_mad_i32_i24 v39, v51, s96, v39
	v_lshl_add_u64 v[14:15], v[16:17], 0, s[4:5]
	v_lshl_add_u64 v[18:19], v[20:21], 0, s[4:5]
	v_lshl_add_u64 v[30:31], v[32:33], 0, s[4:5]
	v_lshl_add_u64 v[38:39], v[38:39], 0, s[4:5]
	s_or_b32 s4, s2, s64
	s_ashr_i32 s5, s4, 31
	s_lshl_b64 s[4:5], s[4:5], 2
	s_waitcnt lgkmcnt(0)
	s_add_u32 s78, s74, s4
	s_addc_u32 s79, s75, s5
	s_load_dword s98, s[78:79], 0x0
	s_load_dword s99, s[78:79], 0x20
	s_mov_b32 s76, 0xb2a5705f
	s_mov_b32 s77, 0x42ce8ed0
	s_mov_b32 s58, 0xc2b17218
	s_mov_b32 s25, 0x3f2aaaab
	s_mov_b32 s72, 0x7f800000
	s_mov_b32 s73, 0x33800000
	v_lshlrev_b32_e32 v40, 1, v104
	v_mov_b32_e32 v41, v1
	v_lshl_add_u64 v[14:15], v[14:15], 0, v[40:41]
	v_lshl_add_u64 v[18:19], v[18:19], 0, v[40:41]
	v_lshl_add_u64 v[30:31], v[30:31], 0, v[40:41]
	v_lshl_add_u64 v[38:39], v[38:39], 0, v[40:41]
	global_load_dwordx4 v[14:17], v[14:15], off
	v_readlane_b32 s4, v254, 38
	global_load_dwordx4 v[18:21], v[18:19], off
	v_readlane_b32 s5, v254, 39
	global_load_dwordx4 v[30:33], v[30:31], off
	v_add_u32_e32 v82, 0x4800, v230
	global_load_dwordx4 v[38:41], v[38:39], off
	s_mov_b32 s53, s64
	s_waitcnt vmcnt(10) lgkmcnt(0)
; __device__ __forceinline__ float softplusf_(float x) { return fmaxf(x, 0.f) + log1pf(expf(-fabsf(x))); }
; __device__ __forceinline__ float log2_gamma(const Args& A, const Frame& F, int l, int dir, int h) {
;     const float x = GIN(12)[(l * 2 + dir) * NH + h];
;     return -softplusf_(-x) * 1.4426950408889634f;
; }
	v_mov_b32_e32 v50, s98
	v_max_f32_e64 v51, -v50, -v50
	v_max_f32_e32 v66, 0, v51
	v_mul_f32_e64 v51, |v50|, s59
	v_fma_f32 v52, |v50|, s59, -v51
	v_rndne_f32_e32 v53, v51
	v_fma_f32 v52, |v50|, s76, v52
	v_sub_f32_e32 v51, v51, v53
	v_add_f32_e32 v51, v51, v52
	v_exp_f32_e32 v51, v51
	v_cvt_i32_f32_e32 v52, v53
	v_cmp_ngt_f32_e64 s[74:75], |v50|, s77
	v_ldexp_f32 v51, v51, v52
	s_nop 0
	v_cndmask_b32_e64 v51, 0, v51, s[74:75]
	v_cmp_nlt_f32_e64 s[74:75], |v50|, s58
	s_nop 1
	v_cndmask_b32_e64 v67, v182, v51, s[74:75]
	v_add_f32_e32 v52, 1.0, v67
	v_add_f32_e32 v50, -1.0, v52
	v_sub_f32_e32 v51, v50, v52
	v_add_f32_e32 v51, 1.0, v51
	v_sub_f32_e32 v50, v67, v50
	v_add_f32_e32 v53, v50, v51
	v_frexp_mant_f32_e32 v50, v52
	v_cmp_gt_f32_e64 s[74:75], s25, v50
	v_cvt_f64_f32_e32 v[50:51], v52
	v_frexp_exp_i32_f64_e32 v50, v[50:51]
	v_subbrev_co_u32_e64 v58, s[74:75], 0, v50, s[74:75]
	v_sub_u32_e32 v50, 0, v58
	v_ldexp_f32 v51, v52, v50
	v_add_f32_e32 v52, -1.0, v51
	v_add_f32_e32 v54, 1.0, v51
	v_ldexp_f32 v50, v53, v50
	v_add_f32_e32 v53, 1.0, v52
	v_add_f32_e32 v55, -1.0, v54
	v_sub_f32_e32 v53, v51, v53
	v_sub_f32_e32 v51, v51, v55
	v_add_f32_e32 v53, v50, v53
	v_add_f32_e32 v50, v50, v51
	v_add_f32_e32 v59, v54, v50
	v_rcp_f32_e32 v61, v59
	v_sub_f32_e32 v51, v54, v59
	v_add_f32_e32 v60, v50, v51
	v_add_f32_e32 v51, v52, v53
	v_mul_f32_e32 v63, v51, v61
	v_sub_f32_e32 v50, v52, v51
	v_mul_f32_e32 v52, v59, v63
	v_fma_f32 v54, v63, v59, -v52
	v_fmac_f32_e32 v54, v63, v60
	v_add_f32_e32 v62, v53, v50
	v_add_f32_e32 v50, v52, v54
	v_sub_f32_e32 v53, v51, v50
	v_pk_add_f32 v[56:57], v[50:51], v[52:53] neg_lo:[0,1] neg_hi:[0,1]
	v_mov_b32_e32 v55, v50
	v_pk_add_f32 v[50:51], v[56:57], v[54:55] neg_lo:[0,1] neg_hi:[0,1]
	v_cmp_neq_f32_e64 s[74:75], s72, v67
	v_add_f32_e32 v51, v62, v51
	v_add_f32_e32 v50, v50, v51
	v_add_f32_e32 v51, v53, v50
	v_mul_f32_e32 v62, v61, v51
	v_mul_f32_e32 v52, v59, v62
	v_fma_f32 v54, v62, v59, -v52
	v_fmac_f32_e32 v54, v62, v60
	v_sub_f32_e32 v53, v53, v51
	v_add_f32_e32 v59, v50, v53
	v_add_f32_e32 v50, v52, v54
	v_sub_f32_e32 v53, v51, v50
	v_pk_add_f32 v[56:57], v[50:51], v[52:53] neg_lo:[0,1] neg_hi:[0,1]
	v_mov_b32_e32 v55, v50
	v_pk_add_f32 v[50:51], v[56:57], v[54:55] neg_lo:[0,1] neg_hi:[0,1]
	s_nop 0
	v_add_f32_e32 v51, v59, v51
	v_add_f32_e32 v50, v50, v51
	v_add_f32_e32 v51, v63, v62
	v_add_f32_e32 v50, v53, v50
	v_sub_f32_e32 v52, v51, v63
	v_mul_f32_e32 v50, v61, v50
	v_sub_f32_e32 v52, v62, v52
	v_add_f32_e32 v52, v52, v50
	v_add_f32_e32 v54, v51, v52
	v_mul_f32_e32 v55, v54, v54
	v_fmamk_f32 v50, v55, 0x3e9b6dac, v171
	v_fmaak_f32 v141, v55, v50, 0x3f2aaada
	v_cvt_f32_i32_e32 v50, v58
	v_sub_f32_e32 v51, v54, v51
	v_sub_f32_e32 v51, v52, v51
	v_ldexp_f32 v56, v51, 1
	v_mul_f32_e32 v51, v54, v55
	v_ldexp_f32 v53, v54, 1
	v_pk_mul_f32 v[54:55], v[50:51], v[140:141]
	s_nop 0
	v_fma_f32 v52, v50, s29, -v54
	v_fmac_f32_e32 v52, 0xb102e308, v50
	v_pk_add_f32 v[50:51], v[54:55], v[52:53]
	s_nop 0
	v_sub_f32_e32 v53, v51, v53
	v_sub_f32_e32 v53, v55, v53
	v_add_f32_e32 v57, v56, v53
	v_mov_b32_e32 v56, v54
	v_pk_add_f32 v[54:55], v[50:51], v[54:55] neg_lo:[0,1] neg_hi:[0,1]
	v_pk_add_f32 v[58:59], v[50:51], v[56:57]
	v_mov_b32_e32 v53, v50
	v_mov_b32_e32 v55, v59
	v_pk_add_f32 v[60:61], v[52:53], v[54:55] neg_lo:[0,1] neg_hi:[0,1]
	v_pk_add_f32 v[52:53], v[52:53], v[54:55]
	v_mov_b32_e32 v64, v51
	v_pk_add_f32 v[54:55], v[52:53], v[50:51] op_sel:[1,0] op_sel_hi:[0,1] neg_lo:[0,1] neg_hi:[0,1]
	v_pk_add_f32 v[62:63], v[58:59], v[54:55] op_sel_hi:[1,0] neg_lo:[0,1] neg_hi:[0,1]
	v_mov_b32_e32 v58, v59
	v_mov_b32_e32 v59, v53
	v_mov_b32_e32 v65, v54
	v_pk_add_f32 v[54:55], v[58:59], v[64:65] neg_lo:[0,1] neg_hi:[0,1]
	v_mov_b32_e32 v56, v57
	v_mov_b32_e32 v57, v50
	v_pk_add_f32 v[50:51], v[56:57], v[54:55] neg_lo:[0,1] neg_hi:[0,1]
	v_mov_b32_e32 v62, v60
	v_pk_add_f32 v[54:55], v[62:63], v[50:51]
	v_mov_b32_e32 v61, v53
	v_pk_add_f32 v[56:57], v[54:55], v[54:55] op_sel:[0,1] op_sel_hi:[1,0]
	s_nop 0
	v_pk_add_f32 v[52:53], v[52:53], v[56:57] op_sel:[1,0] op_sel_hi:[0,1]
	v_mov_b32_e32 v55, v52
	v_pk_add_f32 v[58:59], v[54:55], v[60:61] neg_lo:[0,1] neg_hi:[0,1]
	v_mov_b32_e32 v51, v56
	v_sub_f32_e32 v53, v54, v58
	v_pk_add_f32 v[50:51], v[50:51], v[58:59] neg_lo:[0,1] neg_hi:[0,1]
	v_sub_f32_e32 v53, v60, v53
	v_add_f32_e32 v50, v50, v53
	v_add_f32_e32 v50, v50, v51
	v_add_f32_e32 v50, v52, v50
	v_cndmask_b32_e64 v50, v182, v50, s[74:75]
	v_cmp_lt_f32_e64 s[74:75], |v67|, s73
	v_mov_b32_e32 v51, s99
	v_mul_f32_e64 v52, |v51|, s59
	v_fma_f32 v53, |v51|, s59, -v52
	v_rndne_f32_e32 v54, v52
	v_fma_f32 v53, |v51|, s76, v53
	v_sub_f32_e32 v52, v52, v54
	v_add_f32_e32 v52, v52, v53
	v_exp_f32_e32 v52, v52
	v_cvt_i32_f32_e32 v53, v54
	v_cndmask_b32_e64 v50, v50, v67, s[74:75]
	v_cmp_ngt_f32_e64 s[74:75], |v51|, s77
	v_add_f32_e32 v50, v66, v50
	v_ldexp_f32 v52, v52, v53
	v_cndmask_b32_e64 v52, 0, v52, s[74:75]
	v_cmp_nlt_f32_e64 s[74:75], |v51|, s58
	v_mul_f32_e32 v66, 0xbfb8aa3b, v50
	v_max_f32_e64 v50, -v51, -v51
	v_cndmask_b32_e64 v51, v182, v52, s[74:75]
	v_add_f32_e32 v54, 1.0, v51
	v_add_f32_e32 v52, -1.0, v54
	v_sub_f32_e32 v53, v52, v54
	v_add_f32_e32 v53, 1.0, v53
	v_sub_f32_e32 v52, v51, v52
	v_add_f32_e32 v55, v52, v53
	v_frexp_mant_f32_e32 v52, v54
	v_cmp_gt_f32_e64 s[74:75], s25, v52
	v_cvt_f64_f32_e32 v[52:53], v54
	v_frexp_exp_i32_f64_e32 v52, v[52:53]
	v_subbrev_co_u32_e64 v52, s[74:75], 0, v52, s[74:75]
	v_sub_u32_e32 v53, 0, v52
	v_ldexp_f32 v54, v54, v53
	v_add_f32_e32 v56, -1.0, v54
	v_ldexp_f32 v53, v55, v53
	v_add_f32_e32 v55, 1.0, v56
	v_sub_f32_e32 v55, v54, v55
	v_add_f32_e32 v57, v53, v55
; #define LAS __attribute__((address_space(3)))
; __device__ __forceinline__ unsigned pk2(float lo, float hi) { const f32x2_t v = {lo, hi}; const bf16v2_t b = __builtin_convertvector(v, bf16v2_t); return __builtin_bit_cast(unsigned, b); }
; __device__ __forceinline__ void ret_out_phase(const Args& A, Frame& F, int l, bool lastl, bf16_t* ARET, bf16_t* ALRU) {
;     ...
;             for (int jp = 0; jp < 4; ++jp) {
;                 f32x4 c0 = (f32x4){0.f, 0.f, 0.f, 0.f}, c1 = c0;
; #pragma unroll
;                 for (int ks = 0; ks < 2; ++ks) {
;                     const bf16x8 k0 = *(const LAS bf16x8*)(ks_ + (32 * jp + fr) * 72 + 32 * ks + 8 * fq);
;                     const bf16x8 k1 = *(const LAS bf16x8*)(ks_ + (32 * jp + 16 + fr) * 72 + 32 * ks + 8 * fq);
;                     c0 = __builtin_amdgcn_mfma_f32_16x16x32_bf16(k0, qf[ks], c0, 0, 0, 0);
;                     c1 = __builtin_amdgcn_mfma_f32_16x16x32_bf16(k1, qf[ks], c1, 0, 0, 0);
;                 }
;                 float v[8];
; #pragma unroll
;                 for (int r = 0; r < 4; ++r) {
;                     const int j0 = 32 * jp + 4 * fq + r, j1 = j0 + 16;
;                     const int d0 = i_loc - j0, d1 = i_loc - j1;
;                     v[r] = c0[r] * (d0 >= 0 ? exp2f((float)d0 * l2f) : exp2f((float)(-d0) * l2b));
;                     v[4 + r] = c1[r] * (d1 >= 0 ? exp2f((float)d1 * l2f) : exp2f((float)(-d1) * l2b));
;                 }
;                 u32x4 pv; pv[0] = pk2(v[0], v[1]); pv[1] = pk2(v[2], v[3]); pv[2] = pk2(v[4], v[5]); pv[3] = pk2(v[6], v[7]);
;                 pa[jp] = __builtin_bit_cast(bf16x8, pv);
;             }
	v_add_f32_e32 v55, 1.0, v54
	v_add_f32_e32 v58, -1.0, v55
	v_sub_f32_e32 v54, v54, v58
	v_add_f32_e32 v53, v53, v54
	v_add_f32_e32 v62, v55, v53
	v_rcp_f32_e32 v63, v62
	v_sub_f32_e32 v54, v55, v62
	v_add_f32_e32 v55, v56, v57
	v_add_f32_e32 v53, v53, v54
	v_mul_f32_e32 v65, v55, v63
	v_sub_f32_e32 v54, v56, v55
	v_mul_f32_e32 v56, v62, v65
	v_fma_f32 v58, v65, v62, -v56
	v_fmac_f32_e32 v58, v65, v53
	v_add_f32_e32 v64, v57, v54
	v_add_f32_e32 v54, v56, v58
	v_sub_f32_e32 v57, v55, v54
	v_pk_add_f32 v[60:61], v[54:55], v[56:57] neg_lo:[0,1] neg_hi:[0,1]
	v_mov_b32_e32 v59, v54
	v_pk_add_f32 v[54:55], v[60:61], v[58:59] neg_lo:[0,1] neg_hi:[0,1]
	v_cvt_f32_i32_e32 v52, v52
	v_add_f32_e32 v55, v64, v55
	v_add_f32_e32 v54, v54, v55
	v_add_f32_e32 v55, v57, v54
	v_mul_f32_e32 v64, v63, v55
	v_mul_f32_e32 v56, v62, v64
	v_fma_f32 v58, v64, v62, -v56
	v_fmac_f32_e32 v58, v64, v53
	v_sub_f32_e32 v53, v57, v55
	v_add_f32_e32 v53, v54, v53
	v_add_f32_e32 v54, v56, v58
	v_sub_f32_e32 v57, v55, v54
	v_pk_add_f32 v[60:61], v[54:55], v[56:57] neg_lo:[0,1] neg_hi:[0,1]
	v_mov_b32_e32 v59, v54
	v_pk_add_f32 v[54:55], v[60:61], v[58:59] neg_lo:[0,1] neg_hi:[0,1]
	v_cmp_neq_f32_e64 s[74:75], s72, v51
	v_add_f32_e32 v53, v53, v55
	v_add_f32_e32 v53, v54, v53
	v_add_f32_e32 v54, v65, v64
	v_add_f32_e32 v53, v57, v53
	v_sub_f32_e32 v55, v54, v65
	v_mul_f32_e32 v53, v63, v53
	v_sub_f32_e32 v55, v64, v55
	v_add_f32_e32 v53, v55, v53
	v_add_f32_e32 v56, v54, v53
	v_mul_f32_e32 v57, v56, v56
	v_sub_f32_e32 v54, v56, v54
	v_fmamk_f32 v55, v57, 0x3e9b6dac, v171
	v_sub_f32_e32 v53, v53, v54
	v_fmaak_f32 v141, v57, v55, 0x3f2aaada
	v_ldexp_f32 v58, v53, 1
	v_mul_f32_e32 v53, v56, v57
	v_ldexp_f32 v55, v56, 1
	v_pk_mul_f32 v[56:57], v[52:53], v[140:141]
	v_max_f32_e32 v50, 0, v50
	v_fma_f32 v54, v52, s29, -v56
	v_fmac_f32_e32 v54, 0xb102e308, v52
	v_pk_add_f32 v[52:53], v[56:57], v[54:55]
	s_nop 0
	v_sub_f32_e32 v55, v53, v55
	v_sub_f32_e32 v55, v57, v55
	v_add_f32_e32 v59, v58, v55
	v_mov_b32_e32 v58, v56
	v_pk_add_f32 v[56:57], v[52:53], v[56:57] neg_lo:[0,1] neg_hi:[0,1]
	v_pk_add_f32 v[60:61], v[52:53], v[58:59]
	v_mov_b32_e32 v55, v52
	v_mov_b32_e32 v57, v61
	v_pk_add_f32 v[62:63], v[54:55], v[56:57] neg_lo:[0,1] neg_hi:[0,1]
	v_pk_add_f32 v[54:55], v[54:55], v[56:57]
	v_mov_b32_e32 v68, v53
	v_pk_add_f32 v[56:57], v[54:55], v[52:53] op_sel:[1,0] op_sel_hi:[0,1] neg_lo:[0,1] neg_hi:[0,1]
	v_pk_add_f32 v[64:65], v[60:61], v[56:57] op_sel_hi:[1,0] neg_lo:[0,1] neg_hi:[0,1]
	v_mov_b32_e32 v60, v61
	v_mov_b32_e32 v61, v55
	v_mov_b32_e32 v69, v56
	v_pk_add_f32 v[56:57], v[60:61], v[68:69] neg_lo:[0,1] neg_hi:[0,1]
	v_mov_b32_e32 v58, v59
	v_mov_b32_e32 v59, v52
	v_pk_add_f32 v[52:53], v[58:59], v[56:57] neg_lo:[0,1] neg_hi:[0,1]
	v_mov_b32_e32 v64, v62
	v_pk_add_f32 v[56:57], v[64:65], v[52:53]
	v_mov_b32_e32 v63, v55
	v_pk_add_f32 v[58:59], v[56:57], v[56:57] op_sel:[0,1] op_sel_hi:[1,0]
	s_nop 0
	v_pk_add_f32 v[54:55], v[54:55], v[58:59] op_sel:[1,0] op_sel_hi:[0,1]
	v_mov_b32_e32 v57, v54
	v_pk_add_f32 v[60:61], v[56:57], v[62:63] neg_lo:[0,1] neg_hi:[0,1]
	v_mov_b32_e32 v53, v58
	v_sub_f32_e32 v55, v56, v60
	v_pk_add_f32 v[52:53], v[52:53], v[60:61] neg_lo:[0,1] neg_hi:[0,1]
	v_sub_f32_e32 v55, v62, v55
	v_add_f32_e32 v52, v52, v55
	v_add_f32_e32 v52, v52, v53
	v_add_f32_e32 v52, v54, v52
	v_cndmask_b32_e64 v52, v182, v52, s[74:75]
	v_cmp_lt_f32_e64 s[74:75], |v51|, s73
	s_nop 1
	v_cndmask_b32_e64 v51, v52, v51, s[74:75]
	v_add_f32_e32 v50, v50, v51
	v_mul_f32_e32 v67, 0xbfb8aa3b, v50
	ds_read_b128 v[50:53], v143
	ds_read_b128 v[54:57], v143 offset:2304
	s_waitcnt lgkmcnt(1)
	v_mfma_f32_16x16x32_bf16 v[50:53], v[50:53], v[46:49], 0
	ds_read_b128 v[58:61], v143 offset:64
	ds_read_b128 v[62:65], v143 offset:2368
	s_waitcnt lgkmcnt(1)
	v_mfma_f32_16x16x32_bf16 v[50:53], v[58:61], v[42:45], v[50:53]
	v_mul_f32_e32 v58, v67, v144
	v_mul_f32_e32 v59, v66, v145
	v_cndmask_b32_e64 v58, v59, v58, s[4:5]
	v_cmp_gt_f32_e64 s[74:75], s3, v58
	v_readlane_b32 s4, v254, 36
	v_mul_f32_e32 v60, v66, v147
	v_cndmask_b32_e64 v59, 0, v183, s[74:75]
	v_add_f32_e32 v58, v58, v59
	v_exp_f32_e32 v58, v58
	v_cndmask_b32_e64 v59, 0, v184, s[74:75]
	v_readlane_b32 s5, v254, 37
	v_mul_f32_e32 v61, v67, v148
	v_ldexp_f32 v58, v58, v59
	v_mul_f32_e32 v59, v67, v146
	v_cndmask_b32_e64 v59, v60, v59, s[4:5]
	v_cmp_gt_f32_e64 s[74:75], s3, v59
	v_readlane_b32 s4, v254, 40
	v_readlane_b32 s5, v254, 41
	v_cndmask_b32_e64 v60, 0, v183, s[74:75]
	v_add_f32_e32 v59, v59, v60
	v_exp_f32_e32 v59, v59
	v_cndmask_b32_e64 v60, 0, v184, s[74:75]
	v_mfma_f32_16x16x32_bf16 v[54:57], v[54:57], v[46:49], 0
	v_ldexp_f32 v60, v59, v60
	v_mul_f32_e32 v59, v66, v149
	v_cndmask_b32_e64 v59, v59, v61, s[4:5]
	v_cmp_gt_f32_e64 s[74:75], s3, v59
	v_readlane_b32 s4, v254, 42
	v_readlane_b32 s5, v254, 43
	v_cndmask_b32_e64 v61, 0, v183, s[74:75]
	v_add_f32_e32 v59, v59, v61
	v_exp_f32_e32 v59, v59
	v_cndmask_b32_e64 v61, 0, v184, s[74:75]
	s_waitcnt lgkmcnt(0)
; #define LAS __attribute__((address_space(3)))
; __device__ __forceinline__ unsigned pk2(float lo, float hi) { const f32x2_t v = {lo, hi}; const bf16v2_t b = __builtin_convertvector(v, bf16v2_t); return __builtin_bit_cast(unsigned, b); }
; __device__ __forceinline__ void ret_out_phase(const Args& A, Frame& F, int l, bool lastl, bf16_t* ARET, bf16_t* ALRU) {
;     ...
;             for (int jp = 0; jp < 4; ++jp) {
;                 f32x4 c0 = (f32x4){0.f, 0.f, 0.f, 0.f}, c1 = c0;
; #pragma unroll
;                 for (int ks = 0; ks < 2; ++ks) {
;                     const bf16x8 k0 = *(const LAS bf16x8*)(ks_ + (32 * jp + fr) * 72 + 32 * ks + 8 * fq);
;                     const bf16x8 k1 = *(const LAS bf16x8*)(ks_ + (32 * jp + 16 + fr) * 72 + 32 * ks + 8 * fq);
;                     c0 = __builtin_amdgcn_mfma_f32_16x16x32_bf16(k0, qf[ks], c0, 0, 0, 0);
;                     c1 = __builtin_amdgcn_mfma_f32_16x16x32_bf16(k1, qf[ks], c1, 0, 0, 0);
;                 }
;                 float v[8];
; #pragma unroll
;                 for (int r = 0; r < 4; ++r) {
;                     const int j0 = 32 * jp + 4 * fq + r, j1 = j0 + 16;
;                     const int d0 = i_loc - j0, d1 = i_loc - j1;
;                     v[r] = c0[r] * (d0 >= 0 ? exp2f((float)d0 * l2f) : exp2f((float)(-d0) * l2b));
;                     v[4 + r] = c1[r] * (d1 >= 0 ? exp2f((float)d1 * l2f) : exp2f((float)(-d1) * l2b));
;                 }
;                 u32x4 pv; pv[0] = pk2(v[0], v[1]); pv[1] = pk2(v[2], v[3]); pv[2] = pk2(v[4], v[5]); pv[3] = pk2(v[6], v[7]);
;                 pa[jp] = __builtin_bit_cast(bf16x8, pv);
;             }
	v_mfma_f32_16x16x32_bf16 v[54:57], v[62:65], v[42:45], v[54:57]
	v_ldexp_f32 v59, v59, v61
	v_pk_mul_f32 v[50:51], v[50:51], v[58:59]
	v_mul_f32_e32 v58, v66, v151
	v_mul_f32_e32 v59, v67, v150
	v_cndmask_b32_e64 v58, v58, v59, s[4:5]
	v_cmp_gt_f32_e64 s[74:75], s3, v58
	v_readlane_b32 s4, v254, 44
	v_readlane_b32 s5, v254, 45
	v_cndmask_b32_e64 v59, 0, v183, s[74:75]
	v_add_f32_e32 v58, v58, v59
	v_exp_f32_e32 v58, v58
	v_cndmask_b32_e64 v59, 0, v184, s[74:75]
	v_cvt_pk_bf16_f32 v50, v50, v51
	v_ldexp_f32 v61, v58, v59
	v_mul_f32_e32 v58, v66, v153
	v_mul_f32_e32 v59, v67, v152
	v_cndmask_b32_e64 v58, v58, v59, s[4:5]
	v_cmp_gt_f32_e64 s[74:75], s3, v58
	v_readlane_b32 s4, v254, 46
	v_pk_mul_f32 v[54:55], v[54:55], v[60:61]
	v_cndmask_b32_e64 v59, 0, v183, s[74:75]
	v_add_f32_e32 v58, v58, v59
	v_exp_f32_e32 v58, v58
	v_cndmask_b32_e64 v59, 0, v184, s[74:75]
	v_mul_f32_e32 v60, v67, v154
	v_readlane_b32 s5, v254, 47
	v_ldexp_f32 v58, v58, v59
	v_mul_f32_e32 v59, v66, v155
	v_cndmask_b32_e64 v59, v59, v60, s[4:5]
	v_cmp_gt_f32_e64 s[74:75], s3, v59
	v_readlane_b32 s4, v254, 48
	v_mul_f32_e32 v61, v67, v156
	v_cndmask_b32_e64 v60, 0, v183, s[74:75]
	v_add_f32_e32 v59, v59, v60
	v_exp_f32_e32 v59, v59
	v_cndmask_b32_e64 v60, 0, v184, s[74:75]
	v_readlane_b32 s5, v254, 49
	v_ldexp_f32 v60, v59, v60
	v_mul_f32_e32 v59, v66, v157
	v_cndmask_b32_e64 v59, v59, v61, s[4:5]
	v_cmp_gt_f32_e64 s[74:75], s3, v59
	v_readlane_b32 s4, v254, 50
	v_readlane_b32 s5, v254, 51
	v_cndmask_b32_e64 v61, 0, v183, s[74:75]
	v_add_f32_e32 v59, v59, v61
	v_exp_f32_e32 v59, v59
	v_cndmask_b32_e64 v61, 0, v184, s[74:75]
	v_ldexp_f32 v59, v59, v61
	v_pk_mul_f32 v[52:53], v[52:53], v[58:59]
	v_mul_f32_e32 v58, v66, v159
	v_mul_f32_e32 v59, v67, v158
	v_cndmask_b32_e64 v58, v58, v59, s[4:5]
	v_cmp_gt_f32_e64 s[74:75], s3, v58
	v_cvt_pk_bf16_f32 v51, v52, v53
	v_cvt_pk_bf16_f32 v52, v54, v55
	v_cndmask_b32_e64 v59, 0, v183, s[74:75]
	v_add_f32_e32 v58, v58, v59
	v_exp_f32_e32 v58, v58
	v_cndmask_b32_e64 v59, 0, v184, s[74:75]
	v_readlane_b32 s4, v254, 52
	v_readlane_b32 s5, v254, 53
	v_ldexp_f32 v61, v58, v59
	v_pk_mul_f32 v[56:57], v[56:57], v[60:61]
	s_nop 0
	v_cvt_pk_bf16_f32 v53, v56, v57
	ds_read_b128 v[54:57], v160
	ds_read_b128 v[58:61], v160 offset:2304
	s_waitcnt lgkmcnt(1)
	v_mfma_f32_16x16x32_bf16 v[54:57], v[54:57], v[46:49], 0
	ds_read_b128 v[62:65], v160 offset:64
	ds_read_b128 v[68:71], v160 offset:2368
	s_waitcnt lgkmcnt(1)
	v_mfma_f32_16x16x32_bf16 v[54:57], v[62:65], v[42:45], v[54:57]
	v_mul_f32_e32 v62, v66, v162
	v_mul_f32_e32 v63, v67, v161
	v_cndmask_b32_e64 v62, v62, v63, s[4:5]
	v_cmp_gt_f32_e64 s[74:75], s3, v62
	v_readlane_b32 s4, v254, 54
	v_mul_f32_e32 v64, v67, v163
	v_cndmask_b32_e64 v63, 0, v183, s[74:75]
	v_add_f32_e32 v62, v62, v63
	v_exp_f32_e32 v62, v62
	v_cndmask_b32_e64 v63, 0, v184, s[74:75]
	v_readlane_b32 s5, v254, 55
	v_mul_f32_e32 v65, v67, v165
	v_ldexp_f32 v62, v62, v63
	v_mul_f32_e32 v63, v66, v164
	v_cndmask_b32_e64 v63, v63, v64, s[4:5]
	v_cmp_gt_f32_e64 s[74:75], s3, v63
	v_readlane_b32 s4, v254, 56
	v_readlane_b32 s5, v254, 57
	v_cndmask_b32_e64 v64, 0, v183, s[74:75]
	v_add_f32_e32 v63, v63, v64
	v_exp_f32_e32 v63, v63
	v_cndmask_b32_e64 v64, 0, v184, s[74:75]
	v_mfma_f32_16x16x32_bf16 v[58:61], v[58:61], v[46:49], 0
	v_ldexp_f32 v64, v63, v64
	v_mul_f32_e32 v63, v66, v166
	v_cndmask_b32_e64 v63, v63, v65, s[4:5]
	v_cmp_gt_f32_e64 s[74:75], s3, v63
	v_readlane_b32 s4, v254, 58
	v_readlane_b32 s5, v254, 59
	v_cndmask_b32_e64 v65, 0, v183, s[74:75]
	v_add_f32_e32 v63, v63, v65
	v_exp_f32_e32 v63, v63
	v_cndmask_b32_e64 v65, 0, v184, s[74:75]
	s_waitcnt lgkmcnt(0)
	v_mfma_f32_16x16x32_bf16 v[58:61], v[68:71], v[42:45], v[58:61]
	v_ldexp_f32 v63, v63, v65
	v_pk_mul_f32 v[54:55], v[54:55], v[62:63]
	v_mul_f32_e32 v62, v66, v168
	v_mul_f32_e32 v63, v67, v167
	v_cndmask_b32_e64 v62, v62, v63, s[4:5]
	v_cmp_gt_f32_e64 s[74:75], s3, v62
	v_readlane_b32 s4, v254, 60
	v_readlane_b32 s5, v254, 61
	v_cndmask_b32_e64 v63, 0, v183, s[74:75]
	v_add_f32_e32 v62, v62, v63
	v_exp_f32_e32 v62, v62
	v_cndmask_b32_e64 v63, 0, v184, s[74:75]
	v_cvt_pk_bf16_f32 v54, v54, v55
	v_ldexp_f32 v65, v62, v63
	v_mul_f32_e32 v62, v66, v189
	v_mul_f32_e32 v63, v67, v169
	v_cndmask_b32_e64 v62, v62, v63, s[4:5]
	v_cmp_gt_f32_e64 s[74:75], s3, v62
	v_readlane_b32 s4, v254, 62
	v_pk_mul_f32 v[58:59], v[58:59], v[64:65]
	v_cndmask_b32_e64 v63, 0, v183, s[74:75]
	v_add_f32_e32 v62, v62, v63
	v_exp_f32_e32 v62, v62
	v_cndmask_b32_e64 v63, 0, v184, s[74:75]
	v_mul_f32_e32 v64, v67, v190
	v_readlane_b32 s5, v254, 63
	v_ldexp_f32 v62, v62, v63
	v_mul_f32_e32 v63, v66, v191
	v_cndmask_b32_e64 v63, v63, v64, s[4:5]
	v_cmp_gt_f32_e64 s[74:75], s3, v63
	v_readlane_b32 s4, v255, 0
	v_mul_f32_e32 v65, v67, v192
	v_cndmask_b32_e64 v64, 0, v183, s[74:75]
	v_add_f32_e32 v63, v63, v64
	v_exp_f32_e32 v63, v63
	v_cndmask_b32_e64 v64, 0, v184, s[74:75]
	v_readlane_b32 s5, v255, 1
	v_ldexp_f32 v64, v63, v64
	v_mul_f32_e32 v63, v66, v193
	v_cndmask_b32_e64 v63, v63, v65, s[4:5]
	v_cmp_gt_f32_e64 s[74:75], s3, v63
	v_readlane_b32 s4, v255, 2
	v_readlane_b32 s5, v255, 3
	v_cndmask_b32_e64 v65, 0, v183, s[74:75]
	v_add_f32_e32 v63, v63, v65
	v_exp_f32_e32 v63, v63
	v_cndmask_b32_e64 v65, 0, v184, s[74:75]
	v_ldexp_f32 v63, v63, v65
	v_pk_mul_f32 v[56:57], v[56:57], v[62:63]
	v_mul_f32_e32 v62, v66, v195
	v_mul_f32_e32 v63, v67, v194
	v_cndmask_b32_e64 v62, v62, v63, s[4:5]
	v_cmp_gt_f32_e64 s[74:75], s3, v62
	v_cvt_pk_bf16_f32 v55, v56, v57
	v_cvt_pk_bf16_f32 v56, v58, v59
	v_cndmask_b32_e64 v63, 0, v183, s[74:75]
	v_add_f32_e32 v62, v62, v63
	v_exp_f32_e32 v62, v62
	v_cndmask_b32_e64 v63, 0, v184, s[74:75]
	v_readlane_b32 s4, v255, 4
	v_readlane_b32 s5, v255, 5
	v_ldexp_f32 v65, v62, v63
	v_pk_mul_f32 v[60:61], v[60:61], v[64:65]
	s_nop 0
	v_cvt_pk_bf16_f32 v57, v60, v61
	ds_read_b128 v[58:61], v196
	ds_read_b128 v[62:65], v196 offset:2304
	s_waitcnt lgkmcnt(1)
; #define LAS __attribute__((address_space(3)))
; __device__ __forceinline__ unsigned pk2(float lo, float hi) { const f32x2_t v = {lo, hi}; const bf16v2_t b = __builtin_convertvector(v, bf16v2_t); return __builtin_bit_cast(unsigned, b); }
; __device__ __forceinline__ void ret_out_phase(const Args& A, Frame& F, int l, bool lastl, bf16_t* ARET, bf16_t* ALRU) {
;     ...
;             for (int jp = 0; jp < 4; ++jp) {
;                 f32x4 c0 = (f32x4){0.f, 0.f, 0.f, 0.f}, c1 = c0;
; #pragma unroll
;                 for (int ks = 0; ks < 2; ++ks) {
;                     const bf16x8 k0 = *(const LAS bf16x8*)(ks_ + (32 * jp + fr) * 72 + 32 * ks + 8 * fq);
;                     const bf16x8 k1 = *(const LAS bf16x8*)(ks_ + (32 * jp + 16 + fr) * 72 + 32 * ks + 8 * fq);
;                     c0 = __builtin_amdgcn_mfma_f32_16x16x32_bf16(k0, qf[ks], c0, 0, 0, 0);
;                     c1 = __builtin_amdgcn_mfma_f32_16x16x32_bf16(k1, qf[ks], c1, 0, 0, 0);
;                 }
;                 float v[8];
; #pragma unroll
;                 for (int r = 0; r < 4; ++r) {
;                     const int j0 = 32 * jp + 4 * fq + r, j1 = j0 + 16;
;                     const int d0 = i_loc - j0, d1 = i_loc - j1;
;                     v[r] = c0[r] * (d0 >= 0 ? exp2f((float)d0 * l2f) : exp2f((float)(-d0) * l2b));
;                     v[4 + r] = c1[r] * (d1 >= 0 ? exp2f((float)d1 * l2f) : exp2f((float)(-d1) * l2b));
;                 }
;                 u32x4 pv; pv[0] = pk2(v[0], v[1]); pv[1] = pk2(v[2], v[3]); pv[2] = pk2(v[4], v[5]); pv[3] = pk2(v[6], v[7]);
;                 pa[jp] = __builtin_bit_cast(bf16x8, pv);
;             }
	v_mfma_f32_16x16x32_bf16 v[58:61], v[58:61], v[46:49], 0
	ds_read_b128 v[68:71], v196 offset:64
	ds_read_b128 v[72:75], v196 offset:2368
	s_waitcnt lgkmcnt(1)
	v_mfma_f32_16x16x32_bf16 v[58:61], v[68:71], v[42:45], v[58:61]
	v_mul_f32_e32 v68, v66, v198
	v_mul_f32_e32 v69, v67, v197
	v_cndmask_b32_e64 v68, v68, v69, s[4:5]
	v_cmp_gt_f32_e64 s[74:75], s3, v68
	v_readlane_b32 s4, v255, 6
	v_mul_f32_e32 v70, v67, v199
	v_cndmask_b32_e64 v69, 0, v183, s[74:75]
	v_add_f32_e32 v68, v68, v69
	v_exp_f32_e32 v68, v68
	v_cndmask_b32_e64 v69, 0, v184, s[74:75]
	v_readlane_b32 s5, v255, 7
	v_mul_f32_e32 v71, v67, v201
	v_ldexp_f32 v68, v68, v69
	v_mul_f32_e32 v69, v66, v200
	v_cndmask_b32_e64 v69, v69, v70, s[4:5]
	v_cmp_gt_f32_e64 s[74:75], s3, v69
	v_readlane_b32 s4, v255, 8
	v_readlane_b32 s5, v255, 9
	v_cndmask_b32_e64 v70, 0, v183, s[74:75]
	v_add_f32_e32 v69, v69, v70
	v_exp_f32_e32 v69, v69
	v_cndmask_b32_e64 v70, 0, v184, s[74:75]
	v_mfma_f32_16x16x32_bf16 v[62:65], v[62:65], v[46:49], 0
	v_ldexp_f32 v70, v69, v70
	v_mul_f32_e32 v69, v66, v202
	v_cndmask_b32_e64 v69, v69, v71, s[4:5]
	v_cmp_gt_f32_e64 s[74:75], s3, v69
	v_readlane_b32 s4, v255, 10
	v_readlane_b32 s5, v255, 11
	v_cndmask_b32_e64 v71, 0, v183, s[74:75]
	v_add_f32_e32 v69, v69, v71
	v_exp_f32_e32 v69, v69
	v_cndmask_b32_e64 v71, 0, v184, s[74:75]
	s_waitcnt lgkmcnt(0)
	v_mfma_f32_16x16x32_bf16 v[62:65], v[72:75], v[42:45], v[62:65]
	v_ldexp_f32 v69, v69, v71
	v_pk_mul_f32 v[58:59], v[58:59], v[68:69]
	v_mul_f32_e32 v68, v66, v204
	v_mul_f32_e32 v69, v67, v203
	v_cndmask_b32_e64 v68, v68, v69, s[4:5]
	v_cmp_gt_f32_e64 s[74:75], s3, v68
	v_readlane_b32 s4, v255, 12
	v_readlane_b32 s5, v255, 13
	v_cndmask_b32_e64 v69, 0, v183, s[74:75]
	v_add_f32_e32 v68, v68, v69
	v_exp_f32_e32 v68, v68
	v_cndmask_b32_e64 v69, 0, v184, s[74:75]
	v_cvt_pk_bf16_f32 v58, v58, v59
	v_ldexp_f32 v71, v68, v69
	v_mul_f32_e32 v68, v66, v206
	v_mul_f32_e32 v69, v67, v205
	v_cndmask_b32_e64 v68, v68, v69, s[4:5]
	v_cmp_gt_f32_e64 s[74:75], s3, v68
	v_readlane_b32 s4, v255, 14
	v_pk_mul_f32 v[62:63], v[62:63], v[70:71]
	v_cndmask_b32_e64 v69, 0, v183, s[74:75]
	v_add_f32_e32 v68, v68, v69
	v_exp_f32_e32 v68, v68
	v_cndmask_b32_e64 v69, 0, v184, s[74:75]
	v_mul_f32_e32 v70, v67, v207
	v_readlane_b32 s5, v255, 15
	v_ldexp_f32 v68, v68, v69
	v_mul_f32_e32 v69, v66, v208
	v_cndmask_b32_e64 v69, v69, v70, s[4:5]
	v_cmp_gt_f32_e64 s[74:75], s3, v69
	v_readlane_b32 s4, v255, 16
	v_mul_f32_e32 v71, v67, v209
	v_cndmask_b32_e64 v70, 0, v183, s[74:75]
	v_add_f32_e32 v69, v69, v70
	v_exp_f32_e32 v69, v69
	v_cndmask_b32_e64 v70, 0, v184, s[74:75]
	v_readlane_b32 s5, v255, 17
	v_ldexp_f32 v70, v69, v70
	v_mul_f32_e32 v69, v66, v210
	v_cndmask_b32_e64 v69, v69, v71, s[4:5]
	v_cmp_gt_f32_e64 s[74:75], s3, v69
	v_readlane_b32 s4, v255, 18
	v_readlane_b32 s5, v255, 19
	v_cndmask_b32_e64 v71, 0, v183, s[74:75]
	v_add_f32_e32 v69, v69, v71
	v_exp_f32_e32 v69, v69
	v_cndmask_b32_e64 v71, 0, v184, s[74:75]
	v_ldexp_f32 v69, v69, v71
	v_pk_mul_f32 v[60:61], v[60:61], v[68:69]
	v_mul_f32_e32 v68, v66, v212
	v_mul_f32_e32 v69, v67, v211
	v_cndmask_b32_e64 v68, v68, v69, s[4:5]
	v_cmp_gt_f32_e64 s[74:75], s3, v68
	v_cvt_pk_bf16_f32 v59, v60, v61
	v_cvt_pk_bf16_f32 v60, v62, v63
	v_cndmask_b32_e64 v69, 0, v183, s[74:75]
	v_add_f32_e32 v68, v68, v69
	v_exp_f32_e32 v68, v68
	v_cndmask_b32_e64 v69, 0, v184, s[74:75]
	v_readlane_b32 s4, v255, 20
	v_readlane_b32 s5, v255, 21
	v_ldexp_f32 v71, v68, v69
	v_pk_mul_f32 v[64:65], v[64:65], v[70:71]
	s_nop 0
	v_cvt_pk_bf16_f32 v61, v64, v65
	ds_read_b128 v[62:65], v213
	ds_read_b128 v[68:71], v213 offset:2304
	s_waitcnt lgkmcnt(1)
	v_mfma_f32_16x16x32_bf16 v[62:65], v[62:65], v[46:49], 0
	ds_read_b128 v[72:75], v213 offset:64
	ds_read_b128 v[76:79], v213 offset:2368
	s_waitcnt lgkmcnt(1)
	v_mfma_f32_16x16x32_bf16 v[62:65], v[72:75], v[42:45], v[62:65]
	v_mul_f32_e32 v72, v66, v215
	v_mul_f32_e32 v73, v67, v214
	v_cndmask_b32_e64 v72, v72, v73, s[4:5]
	v_cmp_gt_f32_e64 s[74:75], s3, v72
	v_readlane_b32 s4, v255, 22
	v_mul_f32_e32 v74, v67, v216
	v_cndmask_b32_e64 v73, 0, v183, s[74:75]
	v_add_f32_e32 v72, v72, v73
	v_exp_f32_e32 v72, v72
	v_cndmask_b32_e64 v73, 0, v184, s[74:75]
	v_readlane_b32 s5, v255, 23
	v_mul_f32_e32 v75, v67, v218
	v_ldexp_f32 v72, v72, v73
	v_mul_f32_e32 v73, v66, v217
	v_cndmask_b32_e64 v73, v73, v74, s[4:5]
	v_cmp_gt_f32_e64 s[74:75], s3, v73
	v_readlane_b32 s4, v255, 24
	v_readlane_b32 s5, v255, 25
	v_cndmask_b32_e64 v74, 0, v183, s[74:75]
	v_add_f32_e32 v73, v73, v74
	v_exp_f32_e32 v73, v73
	v_cndmask_b32_e64 v74, 0, v184, s[74:75]
	v_mfma_f32_16x16x32_bf16 v[68:71], v[68:71], v[46:49], 0
	v_ldexp_f32 v74, v73, v74
	v_mul_f32_e32 v73, v66, v219
	v_cndmask_b32_e64 v73, v73, v75, s[4:5]
	v_cmp_gt_f32_e64 s[74:75], s3, v73
	v_readlane_b32 s4, v255, 26
	v_readlane_b32 s5, v255, 27
	v_cndmask_b32_e64 v75, 0, v183, s[74:75]
	v_add_f32_e32 v73, v73, v75
	v_exp_f32_e32 v73, v73
	v_cndmask_b32_e64 v75, 0, v184, s[74:75]
	s_waitcnt lgkmcnt(0)
; #define LAS __attribute__((address_space(3)))
; __device__ __forceinline__ unsigned pk2(float lo, float hi) { const f32x2_t v = {lo, hi}; const bf16v2_t b = __builtin_convertvector(v, bf16v2_t); return __builtin_bit_cast(unsigned, b); }
; __device__ __forceinline__ void ret_out_phase(const Args& A, Frame& F, int l, bool lastl, bf16_t* ARET, bf16_t* ALRU) {
;     ...
;                     const int j0 = 32 * jp + 4 * fq + r, j1 = j0 + 16;
;                     const int d0 = i_loc - j0, d1 = i_loc - j1;
;                     v[r] = c0[r] * (d0 >= 0 ? exp2f((float)d0 * l2f) : exp2f((float)(-d0) * l2b));
;                     v[4 + r] = c1[r] * (d1 >= 0 ? exp2f((float)d1 * l2f) : exp2f((float)(-d1) * l2b));
;                 }
;                 u32x4 pv; pv[0] = pk2(v[0], v[1]); pv[1] = pk2(v[2], v[3]); pv[2] = pk2(v[4], v[5]); pv[3] = pk2(v[6], v[7]);
;                 pa[jp] = __builtin_bit_cast(bf16x8, pv);
;             }
;         }
;         bf16x8 qF[2], qB[2];
;         {
;             const int il = 16 * w + fr;
;             const float sF = exp2f((float)(il + 1) * l2f), sB = exp2f((float)(128 - il) * l2b);
; #pragma unroll
;             for (int ks = 0; ks < 2; ++ks) { qF[ks] = scale1(qf[ks], sF); qB[ks] = scale1(qf[ks], sB); }
;         }
;         f32x4 O[8];
; #pragma unroll
;         for (int dvt = 0; dvt < 8; ++dvt) {
;             f32x4 o = (f32x4){0.f, 0.f, 0.f, 0.f};
; #pragma unroll
;             for (int jp = 0; jp < 4; ++jp) {
;                 const u32x2 lo = *(const LAS u32x2*)(vts + (16 * dvt + fr) * 136 + 32 * jp + 4 * fq);
;                 const u32x2 hi = *(const LAS u32x2*)(vts + (16 * dvt + fr) * 136 + 32 * jp + 16 + 4 * fq);
;                 u32x4 bv; bv[0] = lo.x; bv[1] = lo.y; bv[2] = hi.x; bv[3] = hi.y;
;                 o = __builtin_amdgcn_mfma_f32_16x16x32_bf16(pa[jp], __builtin_bit_cast(bf16x8, bv), o, 0, 0, 0);
	v_mfma_f32_16x16x32_bf16 v[68:71], v[76:79], v[42:45], v[68:71]
	v_ldexp_f32 v73, v73, v75
	v_pk_mul_f32 v[62:63], v[62:63], v[72:73]
	v_mul_f32_e32 v72, v66, v221
	v_mul_f32_e32 v73, v67, v220
	v_cndmask_b32_e64 v72, v72, v73, s[4:5]
	v_cmp_gt_f32_e64 s[74:75], s3, v72
	v_readlane_b32 s4, v255, 28
	v_readlane_b32 s5, v255, 29
	v_cndmask_b32_e64 v73, 0, v183, s[74:75]
	v_add_f32_e32 v72, v72, v73
	v_exp_f32_e32 v72, v72
	v_cndmask_b32_e64 v73, 0, v184, s[74:75]
	v_cvt_pk_bf16_f32 v62, v62, v63
	v_ldexp_f32 v75, v72, v73
	v_mul_f32_e32 v72, v66, v223
	v_mul_f32_e32 v73, v67, v222
	v_cndmask_b32_e64 v72, v72, v73, s[4:5]
	v_cmp_gt_f32_e64 s[74:75], s3, v72
	v_pk_mul_f32 v[68:69], v[68:69], v[74:75]
	v_mul_f32_e32 v74, v67, v224
	v_cndmask_b32_e64 v73, 0, v183, s[74:75]
	v_add_f32_e32 v72, v72, v73
	v_exp_f32_e32 v72, v72
	v_cndmask_b32_e64 v73, 0, v184, s[74:75]
	v_mul_f32_e32 v75, v67, v226
	v_ldexp_f32 v72, v72, v73
	v_mul_f32_e32 v73, v66, v225
	v_cndmask_b32_e64 v73, v73, v74, s[66:67]
	v_cmp_gt_f32_e64 s[74:75], s3, v73
	s_nop 1
	v_cndmask_b32_e64 v74, 0, v183, s[74:75]
	v_add_f32_e32 v73, v73, v74
	v_exp_f32_e32 v73, v73
	v_cndmask_b32_e64 v74, 0, v184, s[74:75]
	v_ldexp_f32 v74, v73, v74
	v_mul_f32_e32 v73, v66, v227
	v_cndmask_b32_e64 v73, v73, v75, s[68:69]
	v_cmp_gt_f32_e64 s[74:75], s3, v73
	s_nop 1
	v_cndmask_b32_e64 v75, 0, v183, s[74:75]
	v_add_f32_e32 v73, v73, v75
	v_exp_f32_e32 v73, v73
	v_cndmask_b32_e64 v75, 0, v184, s[74:75]
	v_ldexp_f32 v73, v73, v75
	v_pk_mul_f32 v[64:65], v[64:65], v[72:73]
	v_mul_f32_e32 v72, v66, v229
	v_mul_f32_e32 v73, v67, v228
	v_cndmask_b32_e64 v72, v72, v73, s[70:71]
	v_cmp_gt_f32_e64 s[74:75], s3, v72
	v_cvt_pk_bf16_f32 v63, v64, v65
	v_cvt_pk_bf16_f32 v64, v68, v69
	v_cndmask_b32_e64 v73, 0, v183, s[74:75]
	v_mul_f32_e32 v68, v66, v103
	v_add_f32_e32 v72, v72, v73
	v_cndmask_b32_e64 v73, 0, v184, s[74:75]
	v_cmp_gt_f32_e64 s[74:75], s3, v68
	v_exp_f32_e32 v72, v72
	v_and_b32_e32 v69, 0xffff0000, v46
	v_cndmask_b32_e64 v68, 0, v183, s[74:75]
	v_fmac_f32_e32 v68, v66, v103
	v_exp_f32_e32 v66, v68
	v_ldexp_f32 v75, v72, v73
	v_cndmask_b32_e64 v68, 0, v184, s[74:75]
	v_pk_mul_f32 v[70:71], v[70:71], v[74:75]
	v_ldexp_f32 v74, v66, v68
	v_mul_f32_e32 v66, v67, v105
	v_cmp_gt_f32_e64 s[74:75], s3, v66
	v_lshlrev_b32_e32 v68, 16, v46
	v_cvt_pk_bf16_f32 v65, v70, v71
	v_cndmask_b32_e64 v66, 0, v183, s[74:75]
	v_fmac_f32_e32 v66, v67, v105
	v_exp_f32_e32 v66, v66
	v_cndmask_b32_e64 v67, 0, v184, s[74:75]
	v_ldexp_f32 v76, v66, v67
	v_pk_mul_f32 v[66:67], v[74:75], v[68:69] op_sel_hi:[0,1]
	v_pk_mul_f32 v[68:69], v[76:77], v[68:69] op_sel_hi:[0,1]
	v_cvt_pk_bf16_f32 v46, v68, v69
	v_lshlrev_b32_e32 v68, 16, v47
	v_and_b32_e32 v69, 0xffff0000, v47
	v_pk_mul_f32 v[70:71], v[74:75], v[68:69] op_sel_hi:[0,1]
	v_cvt_pk_bf16_f32 v66, v66, v67
	v_cvt_pk_bf16_f32 v67, v70, v71
	v_pk_mul_f32 v[68:69], v[76:77], v[68:69] op_sel_hi:[0,1]
	v_lshlrev_b32_e32 v70, 16, v48
	v_and_b32_e32 v71, 0xffff0000, v48
	v_cvt_pk_bf16_f32 v47, v68, v69
	v_pk_mul_f32 v[68:69], v[74:75], v[70:71] op_sel_hi:[0,1]
	v_pk_mul_f32 v[70:71], v[76:77], v[70:71] op_sel_hi:[0,1]
	v_cvt_pk_bf16_f32 v48, v70, v71
	v_lshlrev_b32_e32 v70, 16, v49
	v_and_b32_e32 v71, 0xffff0000, v49
	v_pk_mul_f32 v[72:73], v[74:75], v[70:71] op_sel_hi:[0,1]
	v_cvt_pk_bf16_f32 v68, v68, v69
	v_cvt_pk_bf16_f32 v69, v72, v73
	v_pk_mul_f32 v[70:71], v[76:77], v[70:71] op_sel_hi:[0,1]
	v_lshlrev_b32_e32 v72, 16, v42
	v_and_b32_e32 v73, 0xffff0000, v42
	v_cvt_pk_bf16_f32 v49, v70, v71
	v_pk_mul_f32 v[70:71], v[74:75], v[72:73] op_sel_hi:[0,1]
	v_pk_mul_f32 v[72:73], v[76:77], v[72:73] op_sel_hi:[0,1]
	v_cvt_pk_bf16_f32 v42, v72, v73
	v_lshlrev_b32_e32 v72, 16, v43
	v_and_b32_e32 v73, 0xffff0000, v43
	v_pk_mul_f32 v[78:79], v[74:75], v[72:73] op_sel_hi:[0,1]
	v_cvt_pk_bf16_f32 v70, v70, v71
	v_cvt_pk_bf16_f32 v71, v78, v79
	v_pk_mul_f32 v[72:73], v[76:77], v[72:73] op_sel_hi:[0,1]
	v_lshlrev_b32_e32 v78, 16, v44
	v_and_b32_e32 v79, 0xffff0000, v44
	v_cvt_pk_bf16_f32 v43, v72, v73
	v_pk_mul_f32 v[72:73], v[74:75], v[78:79] op_sel_hi:[0,1]
	v_pk_mul_f32 v[78:79], v[76:77], v[78:79] op_sel_hi:[0,1]
	v_cvt_pk_bf16_f32 v44, v78, v79
	v_lshlrev_b32_e32 v78, 16, v45
	v_and_b32_e32 v79, 0xffff0000, v45
	v_pk_mul_f32 v[74:75], v[74:75], v[78:79] op_sel_hi:[0,1]
	v_cvt_pk_bf16_f32 v72, v72, v73
	v_cvt_pk_bf16_f32 v73, v74, v75
	v_pk_mul_f32 v[74:75], v[76:77], v[78:79] op_sel_hi:[0,1]
	v_cvt_pk_bf16_f32 v45, v74, v75
	ds_read2_b64 v[74:77], v82 offset1:4
	ds_read2_b64 v[78:81], v82 offset0:8 offset1:12
	s_waitcnt lgkmcnt(1)
	v_mfma_f32_16x16x32_bf16 v[74:77], v[50:53], v[74:77], 0
	s_waitcnt lgkmcnt(0)
	v_mfma_f32_16x16x32_bf16 v[74:77], v[54:57], v[78:81], v[74:77]
	ds_read2_b64 v[78:81], v82 offset0:16 offset1:20
	s_waitcnt lgkmcnt(0)
	v_mfma_f32_16x16x32_bf16 v[74:77], v[58:61], v[78:81], v[74:77]
	ds_read2_b64 v[78:81], v82 offset0:24 offset1:28
	s_waitcnt lgkmcnt(0)
	v_mfma_f32_16x16x32_bf16 v[74:77], v[62:65], v[78:81], v[74:77]
	ds_read_b128 v[78:81], v231 offset:53248
	ds_read_b128 v[82:85], v232
	s_waitcnt lgkmcnt(1)
	v_mfma_f32_16x16x32_bf16 v[74:77], v[66:69], v[78:81], v[74:77]
	s_waitcnt lgkmcnt(0)
	v_mfma_f32_16x16x32_bf16 v[74:77], v[46:49], v[82:85], v[74:77]
	ds_read_b128 v[78:81], v231 offset:53312
	ds_read_b128 v[82:85], v232 offset:64
	s_waitcnt lgkmcnt(1)
	v_mfma_f32_16x16x32_bf16 v[74:77], v[70:73], v[78:81], v[74:77]
	s_waitcnt lgkmcnt(0)
	v_mfma_f32_16x16x32_bf16 v[74:77], v[42:45], v[82:85], v[74:77]
	v_add_u32_e32 v78, 0x1100, v230
	v_add_u32_e32 v86, 0x4800, v78
	ds_read2_b64 v[78:81], v86 offset1:4
	ds_read2_b64 v[82:85], v86 offset0:8 offset1:12
	s_waitcnt lgkmcnt(1)
; #define LAS __attribute__((address_space(3)))
; __device__ __forceinline__ void ret_out_phase(const Args& A, Frame& F, int l, bool lastl, bf16_t* ARET, bf16_t* ALRU) {
;     ...
;         f32x4 O[8];
; #pragma unroll
;         for (int dvt = 0; dvt < 8; ++dvt) {
;             f32x4 o = (f32x4){0.f, 0.f, 0.f, 0.f};
; #pragma unroll
;             for (int jp = 0; jp < 4; ++jp) {
;                 const u32x2 lo = *(const LAS u32x2*)(vts + (16 * dvt + fr) * 136 + 32 * jp + 4 * fq);
;                 const u32x2 hi = *(const LAS u32x2*)(vts + (16 * dvt + fr) * 136 + 32 * jp + 16 + 4 * fq);
;                 u32x4 bv; bv[0] = lo.x; bv[1] = lo.y; bv[2] = hi.x; bv[3] = hi.y;
;                 o = __builtin_amdgcn_mfma_f32_16x16x32_bf16(pa[jp], __builtin_bit_cast(bf16x8, bv), o, 0, 0, 0);
;             }
; #pragma unroll
;             for (int ks = 0; ks < 2; ++ks) {
;                 const bf16x8 sf = *(const LAS bf16x8*)(sfs + (16 * dvt + fr) * 72 + 32 * ks + 8 * fq);
;                 const bf16x8 sb = *(const LAS bf16x8*)(sbs + (16 * dvt + fr) * 72 + 32 * ks + 8 * fq);
;                 o = __builtin_amdgcn_mfma_f32_16x16x32_bf16(qF[ks], sf, o, 0, 0, 0);
;                 o = __builtin_amdgcn_mfma_f32_16x16x32_bf16(qB[ks], sb, o, 0, 0, 0);
;             }
;             O[dvt] = o;
;             __builtin_amdgcn_sched_barrier(0);
;         }
	v_mfma_f32_16x16x32_bf16 v[78:81], v[50:53], v[78:81], 0
	s_waitcnt lgkmcnt(0)
	v_mfma_f32_16x16x32_bf16 v[78:81], v[54:57], v[82:85], v[78:81]
	ds_read2_b64 v[82:85], v86 offset0:16 offset1:20
	s_waitcnt lgkmcnt(0)
	v_mfma_f32_16x16x32_bf16 v[78:81], v[58:61], v[82:85], v[78:81]
	ds_read2_b64 v[82:85], v86 offset0:24 offset1:28
	s_waitcnt lgkmcnt(0)
	v_mfma_f32_16x16x32_bf16 v[78:81], v[62:65], v[82:85], v[78:81]
	ds_read_b128 v[82:85], v231 offset:55552
	s_waitcnt lgkmcnt(0)
	v_mfma_f32_16x16x32_bf16 v[78:81], v[66:69], v[82:85], v[78:81]
	ds_read_b128 v[82:85], v233
	s_waitcnt lgkmcnt(0)
	v_mfma_f32_16x16x32_bf16 v[78:81], v[46:49], v[82:85], v[78:81]
	ds_read_b128 v[82:85], v231 offset:55616
	s_waitcnt lgkmcnt(0)
	v_mfma_f32_16x16x32_bf16 v[78:81], v[70:73], v[82:85], v[78:81]
	ds_read_b128 v[82:85], v233 offset:64
	s_waitcnt lgkmcnt(0)
	v_mfma_f32_16x16x32_bf16 v[78:81], v[42:45], v[82:85], v[78:81]
	v_add_u32_e32 v82, 0x2200, v230
	v_add_u32_e32 v90, 0x4800, v82
	ds_read2_b64 v[82:85], v90 offset1:4
	ds_read2_b64 v[86:89], v90 offset0:8 offset1:12
	s_waitcnt lgkmcnt(1)
	v_mfma_f32_16x16x32_bf16 v[82:85], v[50:53], v[82:85], 0
	s_waitcnt lgkmcnt(0)
	v_mfma_f32_16x16x32_bf16 v[82:85], v[54:57], v[86:89], v[82:85]
	ds_read2_b64 v[86:89], v90 offset0:16 offset1:20
	s_waitcnt lgkmcnt(0)
	v_mfma_f32_16x16x32_bf16 v[82:85], v[58:61], v[86:89], v[82:85]
	ds_read2_b64 v[86:89], v90 offset0:24 offset1:28
	s_waitcnt lgkmcnt(0)
	v_mfma_f32_16x16x32_bf16 v[82:85], v[62:65], v[86:89], v[82:85]
	ds_read_b128 v[86:89], v231 offset:57856
	s_waitcnt lgkmcnt(0)
	v_mfma_f32_16x16x32_bf16 v[82:85], v[66:69], v[86:89], v[82:85]
	ds_read_b128 v[86:89], v234
	s_waitcnt lgkmcnt(0)
	v_mfma_f32_16x16x32_bf16 v[82:85], v[46:49], v[86:89], v[82:85]
	ds_read_b128 v[86:89], v231 offset:57920
	s_waitcnt lgkmcnt(0)
	v_mfma_f32_16x16x32_bf16 v[82:85], v[70:73], v[86:89], v[82:85]
	ds_read_b128 v[86:89], v234 offset:64
	s_waitcnt lgkmcnt(0)
	v_mfma_f32_16x16x32_bf16 v[82:85], v[42:45], v[86:89], v[82:85]
	v_add_u32_e32 v86, 0x3300, v230
	v_add_u32_e32 v94, 0x4800, v86
	ds_read2_b64 v[86:89], v94 offset1:4
	ds_read2_b64 v[90:93], v94 offset0:8 offset1:12
	s_waitcnt lgkmcnt(1)
	v_mfma_f32_16x16x32_bf16 v[86:89], v[50:53], v[86:89], 0
	s_waitcnt lgkmcnt(0)
	v_mfma_f32_16x16x32_bf16 v[86:89], v[54:57], v[90:93], v[86:89]
	ds_read2_b64 v[90:93], v94 offset0:16 offset1:20
	s_waitcnt lgkmcnt(0)
	v_mfma_f32_16x16x32_bf16 v[86:89], v[58:61], v[90:93], v[86:89]
	ds_read2_b64 v[90:93], v94 offset0:24 offset1:28
	s_waitcnt lgkmcnt(0)
	v_mfma_f32_16x16x32_bf16 v[86:89], v[62:65], v[90:93], v[86:89]
	ds_read_b128 v[90:93], v160 offset:55552
	s_waitcnt lgkmcnt(0)
	v_mfma_f32_16x16x32_bf16 v[86:89], v[66:69], v[90:93], v[86:89]
	ds_read_b128 v[90:93], v235
	s_waitcnt lgkmcnt(0)
	v_mfma_f32_16x16x32_bf16 v[86:89], v[46:49], v[90:93], v[86:89]
	ds_read_b128 v[90:93], v160 offset:55616
	s_waitcnt lgkmcnt(0)
	v_mfma_f32_16x16x32_bf16 v[86:89], v[70:73], v[90:93], v[86:89]
	ds_read_b128 v[90:93], v235 offset:64
	s_waitcnt lgkmcnt(0)
	v_mfma_f32_16x16x32_bf16 v[86:89], v[42:45], v[90:93], v[86:89]
	v_add_u32_e32 v90, 0x4400, v230
	v_add_u32_e32 v98, 0x4800, v90
	ds_read2_b64 v[90:93], v98 offset1:4
	ds_read2_b64 v[94:97], v98 offset0:8 offset1:12
	s_waitcnt lgkmcnt(1)
	v_mfma_f32_16x16x32_bf16 v[90:93], v[50:53], v[90:93], 0
	s_waitcnt lgkmcnt(0)
	v_mfma_f32_16x16x32_bf16 v[90:93], v[54:57], v[94:97], v[90:93]
	ds_read2_b64 v[94:97], v98 offset0:16 offset1:20
	s_waitcnt lgkmcnt(0)
	v_mfma_f32_16x16x32_bf16 v[90:93], v[58:61], v[94:97], v[90:93]
	ds_read2_b64 v[94:97], v98 offset0:24 offset1:28
	s_waitcnt lgkmcnt(0)
	v_mfma_f32_16x16x32_bf16 v[90:93], v[62:65], v[94:97], v[90:93]
	ds_read_b128 v[94:97], v236 offset:53248
	s_waitcnt lgkmcnt(0)
	v_mfma_f32_16x16x32_bf16 v[90:93], v[66:69], v[94:97], v[90:93]
	ds_read_b128 v[94:97], v237
	s_waitcnt lgkmcnt(0)
	v_mfma_f32_16x16x32_bf16 v[90:93], v[46:49], v[94:97], v[90:93]
	ds_read_b128 v[94:97], v236 offset:53312
	s_waitcnt lgkmcnt(0)
	v_mfma_f32_16x16x32_bf16 v[90:93], v[70:73], v[94:97], v[90:93]
	ds_read_b128 v[94:97], v237 offset:64
	s_waitcnt lgkmcnt(0)
	v_mfma_f32_16x16x32_bf16 v[90:93], v[42:45], v[94:97], v[90:93]
	v_add_u32_e32 v94, 0x5500, v230
	v_add_u32_e32 v129, 0x4800, v94
	ds_read2_b64 v[94:97], v129 offset1:4
	ds_read2_b64 v[98:101], v129 offset0:8 offset1:12
	s_waitcnt lgkmcnt(1)
	v_mfma_f32_16x16x32_bf16 v[94:97], v[50:53], v[94:97], 0
	s_waitcnt lgkmcnt(0)
	v_mfma_f32_16x16x32_bf16 v[94:97], v[54:57], v[98:101], v[94:97]
	ds_read2_b64 v[98:101], v129 offset0:16 offset1:20
	s_waitcnt lgkmcnt(0)
	v_mfma_f32_16x16x32_bf16 v[94:97], v[58:61], v[98:101], v[94:97]
	ds_read2_b64 v[98:101], v129 offset0:24 offset1:28
	s_waitcnt lgkmcnt(0)
	v_mfma_f32_16x16x32_bf16 v[94:97], v[62:65], v[98:101], v[94:97]
	ds_read_b128 v[98:101], v238 offset:53248
	s_waitcnt lgkmcnt(0)
	v_mfma_f32_16x16x32_bf16 v[94:97], v[66:69], v[98:101], v[94:97]
	ds_read_b128 v[98:101], v239
	s_waitcnt lgkmcnt(0)
	v_mfma_f32_16x16x32_bf16 v[94:97], v[46:49], v[98:101], v[94:97]
	ds_read_b128 v[98:101], v238 offset:53312
	s_waitcnt lgkmcnt(0)
	v_mfma_f32_16x16x32_bf16 v[94:97], v[70:73], v[98:101], v[94:97]
	ds_read_b128 v[98:101], v239 offset:64
	s_waitcnt lgkmcnt(0)
	v_mfma_f32_16x16x32_bf16 v[94:97], v[42:45], v[98:101], v[94:97]
	v_add_u32_e32 v98, 0x6600, v230
	v_add_u32_e32 v129, 0x4800, v98
	ds_read2_b64 v[98:101], v129 offset1:4
	ds_read2_b64 v[250:253], v129 offset0:8 offset1:12
	s_waitcnt lgkmcnt(1)
	v_mfma_f32_16x16x32_bf16 v[98:101], v[50:53], v[98:101], 0
	s_waitcnt lgkmcnt(0)
; #define LAS __attribute__((address_space(3)))
; __device__ __forceinline__ void ret_out_phase(const Args& A, Frame& F, int l, bool lastl, bf16_t* ARET, bf16_t* ALRU) {
;     ...
;         f32x4 O[8];
; #pragma unroll
;         for (int dvt = 0; dvt < 8; ++dvt) {
;             f32x4 o = (f32x4){0.f, 0.f, 0.f, 0.f};
; #pragma unroll
;             for (int jp = 0; jp < 4; ++jp) {
;                 const u32x2 lo = *(const LAS u32x2*)(vts + (16 * dvt + fr) * 136 + 32 * jp + 4 * fq);
;                 const u32x2 hi = *(const LAS u32x2*)(vts + (16 * dvt + fr) * 136 + 32 * jp + 16 + 4 * fq);
;                 u32x4 bv; bv[0] = lo.x; bv[1] = lo.y; bv[2] = hi.x; bv[3] = hi.y;
;                 o = __builtin_amdgcn_mfma_f32_16x16x32_bf16(pa[jp], __builtin_bit_cast(bf16x8, bv), o, 0, 0, 0);
;             }
; #pragma unroll
;             for (int ks = 0; ks < 2; ++ks) {
;                 const bf16x8 sf = *(const LAS bf16x8*)(sfs + (16 * dvt + fr) * 72 + 32 * ks + 8 * fq);
;                 const bf16x8 sb = *(const LAS bf16x8*)(sbs + (16 * dvt + fr) * 72 + 32 * ks + 8 * fq);
;                 o = __builtin_amdgcn_mfma_f32_16x16x32_bf16(qF[ks], sf, o, 0, 0, 0);
;                 o = __builtin_amdgcn_mfma_f32_16x16x32_bf16(qB[ks], sb, o, 0, 0, 0);
;             }
;             O[dvt] = o;
;             __builtin_amdgcn_sched_barrier(0);
;         }
; #pragma unroll
;         for (int r = 0; r < 4; ++r) {
;             float sm = 0.f;
; #pragma unroll
;             for (int dvt = 0; dvt < 8; ++dvt) sm += O[dvt][r];
;             const float mu = sum16(sm) * (1.f / DV);
;             float q2 = 0.f;
; #pragma unroll
;             for (int dvt = 0; dvt < 8; ++dvt) { const float dd = O[dvt][r] - mu; q2 += dd * dd; }
;             const float rstd = rsqrtf(sum16(q2) * (1.f / DV) + EPS);
	v_mfma_f32_16x16x32_bf16 v[98:101], v[54:57], v[250:253], v[98:101]
	ds_read2_b64 v[250:253], v129 offset0:16 offset1:20
	s_waitcnt lgkmcnt(0)
	v_mfma_f32_16x16x32_bf16 v[98:101], v[58:61], v[250:253], v[98:101]
	ds_read2_b64 v[250:253], v129 offset0:24 offset1:28
	s_waitcnt lgkmcnt(0)
	v_mfma_f32_16x16x32_bf16 v[98:101], v[62:65], v[250:253], v[98:101]
	ds_read_b128 v[250:253], v240 offset:53248
	s_waitcnt lgkmcnt(0)
	v_mfma_f32_16x16x32_bf16 v[98:101], v[66:69], v[250:253], v[98:101]
	ds_read_b128 v[250:253], v241
	s_waitcnt lgkmcnt(0)
	v_mfma_f32_16x16x32_bf16 v[98:101], v[46:49], v[250:253], v[98:101]
	ds_read_b128 v[250:253], v240 offset:53312
	s_waitcnt lgkmcnt(0)
	v_mfma_f32_16x16x32_bf16 v[98:101], v[70:73], v[250:253], v[98:101]
	ds_read_b128 v[250:253], v241 offset:64
	s_waitcnt lgkmcnt(0)
	v_mfma_f32_16x16x32_bf16 v[98:101], v[42:45], v[250:253], v[98:101]
	v_add_u32_e32 v129, 0x4800, v242
	ds_read2_b64 v[250:253], v129 offset1:4
	s_waitcnt lgkmcnt(0)
	v_mfma_f32_16x16x32_bf16 v[50:53], v[50:53], v[250:253], 0
	ds_read2_b64 v[250:253], v129 offset0:8 offset1:12
	s_waitcnt lgkmcnt(0)
	v_mfma_f32_16x16x32_bf16 v[50:53], v[54:57], v[250:253], v[50:53]
	ds_read2_b64 v[54:57], v129 offset0:16 offset1:20
	s_waitcnt lgkmcnt(0)
	v_mfma_f32_16x16x32_bf16 v[50:53], v[58:61], v[54:57], v[50:53]
	ds_read2_b64 v[54:57], v129 offset0:24 offset1:28
	s_waitcnt lgkmcnt(0)
	v_mfma_f32_16x16x32_bf16 v[50:53], v[62:65], v[54:57], v[50:53]
	ds_read_b128 v[54:57], v243 offset:53248
	ds_read_b128 v[58:61], v243 offset:53312
	s_waitcnt lgkmcnt(1)
	v_mfma_f32_16x16x32_bf16 v[50:53], v[66:69], v[54:57], v[50:53]
	ds_read_b128 v[54:57], v244
	ds_read_b128 v[62:65], v244 offset:64
	s_waitcnt lgkmcnt(1)
	v_mfma_f32_16x16x32_bf16 v[46:49], v[46:49], v[54:57], v[50:53]
	v_mfma_f32_16x16x32_bf16 v[46:49], v[70:73], v[58:61], v[46:49]
	s_waitcnt lgkmcnt(0)
	v_mfma_f32_16x16x32_bf16 v[42:45], v[42:45], v[62:65], v[46:49]
	s_nop 5
	v_add_f32_e64 v46, v74, 0
	v_add_f32_e64 v47, v75, 0
	v_mov_b32_e32 v50, v86
	v_pk_add_f32 v[46:47], v[46:47], v[78:79]
	v_mov_b32_e32 v51, v82
	v_pk_add_f32 v[46:47], v[46:47], v[82:83]
	v_mov_b32_e32 v82, v87
	v_pk_add_f32 v[46:47], v[46:47], v[86:87]
	v_mov_b32_e32 v52, v94
	v_pk_add_f32 v[46:47], v[46:47], v[90:91]
	v_mov_b32_e32 v53, v90
	v_pk_add_f32 v[46:47], v[46:47], v[94:95]
	v_mov_b32_e32 v90, v95
	v_pk_add_f32 v[46:47], v[46:47], v[98:99]
	v_mov_b32_e32 v54, v42
	v_pk_add_f32 v[46:47], v[46:47], v[42:43]
	ds_bpermute_b32 v48, v127, v46
	ds_bpermute_b32 v49, v127, v47
	v_mov_b32_e32 v55, v98
	v_mov_b32_e32 v98, v43
	s_mov_b32 s2, 0x358637bd
	s_add_i32 vcc_hi, vcc_hi, s34
	s_waitcnt lgkmcnt(0)
	v_pk_add_f32 v[46:47], v[46:47], v[48:49]
	ds_bpermute_b32 v48, v130, v46
	ds_bpermute_b32 v49, v130, v47
	s_add_i32 s61, s61, s60
	s_cmp_lg_u32 s37, s39
	s_waitcnt lgkmcnt(0)
	v_pk_add_f32 v[46:47], v[46:47], v[48:49]
	ds_bpermute_b32 v48, v131, v46
	ds_bpermute_b32 v49, v131, v47
	s_waitcnt lgkmcnt(0)
	v_pk_add_f32 v[46:47], v[46:47], v[48:49]
	ds_bpermute_b32 v48, v132, v46
	ds_bpermute_b32 v49, v132, v47
	s_waitcnt lgkmcnt(0)
	v_pk_add_f32 v[46:47], v[46:47], v[48:49]
	s_nop 0
	v_pk_mul_f32 v[48:49], v[46:47], s[18:19] op_sel_hi:[1,0]
	v_pk_fma_f32 v[64:65], v[46:47], s[18:19], v[78:79] op_sel_hi:[1,0,1] neg_lo:[1,0,0] neg_hi:[1,0,0]
	v_pk_add_f32 v[50:51], v[50:51], v[48:49] op_sel_hi:[1,0] neg_lo:[0,1] neg_hi:[0,1]
	v_pk_add_f32 v[68:69], v[82:83], v[48:49] op_sel:[0,1] neg_lo:[0,1] neg_hi:[0,1]
	v_pk_fma_f32 v[56:57], v[46:47], s[18:19], v[74:75] op_sel_hi:[1,0,1] neg_lo:[1,0,0] neg_hi:[1,0,0]
	v_pk_mul_f32 v[58:59], v[50:51], v[50:51]
	v_pk_mul_f32 v[46:47], v[64:65], v[64:65]
	v_pk_mul_f32 v[70:71], v[68:69], v[68:69]
	v_pk_add_f32 v[52:53], v[52:53], v[48:49] op_sel_hi:[1,0] neg_lo:[0,1] neg_hi:[0,1]
	v_pk_fma_f32 v[66:67], v[56:57], v[56:57], v[46:47]
	v_pk_add_f32 v[46:47], v[90:91], v[48:49] op_sel:[0,1] neg_lo:[0,1] neg_hi:[0,1]
	v_mov_b32_e32 v75, v58
	v_mov_b32_e32 v58, v71
	v_pk_mul_f32 v[60:61], v[52:53], v[52:53]
	v_pk_mul_f32 v[72:73], v[46:47], v[46:47]
	v_mov_b32_e32 v74, v70
	v_pk_add_f32 v[58:59], v[58:59], v[66:67] op_sel:[0,1] op_sel_hi:[1,0]
	v_pk_add_f32 v[54:55], v[54:55], v[48:49] op_sel_hi:[1,0] neg_lo:[0,1] neg_hi:[0,1]
	v_pk_add_f32 v[42:43], v[98:99], v[48:49] op_sel:[0,1] neg_lo:[0,1] neg_hi:[0,1]
	v_pk_add_f32 v[58:59], v[74:75], v[58:59]
	v_mov_b32_e32 v66, v73
	v_mov_b32_e32 v67, v61
	v_pk_mul_f32 v[62:63], v[54:55], v[54:55]
	v_pk_mul_f32 v[48:49], v[42:43], v[42:43]
	v_pk_add_f32 v[58:59], v[66:67], v[58:59]
	v_mov_b32_e32 v73, v60
	v_pk_add_f32 v[58:59], v[72:73], v[58:59]
	v_mov_b32_e32 v60, v49
	v_mov_b32_e32 v61, v63
	v_pk_add_f32 v[58:59], v[60:61], v[58:59]
	v_mov_b32_e32 v49, v62
	v_pk_add_f32 v[48:49], v[48:49], v[58:59]
	ds_bpermute_b32 v59, v127, v49
	ds_bpermute_b32 v58, v127, v48
	s_waitcnt lgkmcnt(0)
	v_pk_add_f32 v[48:49], v[48:49], v[58:59]
	ds_bpermute_b32 v59, v130, v49
	ds_bpermute_b32 v58, v130, v48
	s_waitcnt lgkmcnt(0)
	v_pk_add_f32 v[48:49], v[48:49], v[58:59]
	ds_bpermute_b32 v59, v131, v49
	ds_bpermute_b32 v58, v131, v48
	s_waitcnt lgkmcnt(0)
	v_pk_add_f32 v[48:49], v[48:49], v[58:59]
	ds_bpermute_b32 v59, v132, v49
	ds_bpermute_b32 v58, v132, v48
	s_waitcnt lgkmcnt(0)
; __device__ __forceinline__ bf16_t f2bf(float f) { return (bf16_t)(pk2(f, 0.f) & 0xffffu); }
; __device__ __forceinline__ void ret_out_phase(const Args& A, Frame& F, int l, bool lastl, bf16_t* ARET, bf16_t* ALRU) {
;     ...
;         for (int r = 0; r < 4; ++r) {
;             float sm = 0.f;
; #pragma unroll
;             for (int dvt = 0; dvt < 8; ++dvt) sm += O[dvt][r];
;             const float mu = sum16(sm) * (1.f / DV);
;             float q2 = 0.f;
; #pragma unroll
;             for (int dvt = 0; dvt < 8; ++dvt) { const float dd = O[dvt][r] - mu; q2 += dd * dd; }
;             const float rstd = rsqrtf(sum16(q2) * (1.f / DV) + EPS);
; #pragma unroll
;             for (int dvt = 0; dvt < 8; ++dvt) os[(16 * w + 4 * fq + r) * 136 + 16 * dvt + fr] = f2bf((O[dvt][r] - mu) * rstd);
;         }
	v_pk_add_f32 v[48:49], v[48:49], v[58:59]
	v_mov_b64_e32 v[58:59], s[2:3]
	v_pk_fma_f32 v[48:49], v[48:49], s[18:19], v[58:59] op_sel_hi:[1,0,0]
	s_mov_b32 s2, 0xfcc8000
	v_mul_f32_e32 v60, 0x4b800000, v49
	v_cmp_gt_f32_e64 s[74:75], s33, v49
	s_nop 1
	v_cndmask_b32_e64 v49, v49, v60, s[74:75]
	v_rsq_f32_e32 v49, v49
	s_nop 0
	v_mul_f32_e32 v60, 0x45800000, v49
	v_cndmask_b32_e64 v49, v49, v60, s[74:75]
	v_mul_f32_e32 v50, v50, v49
	v_cvt_pk_bf16_f32 v50, v50, s0
	ds_write_b16 v249, v50 offset:96
	v_mul_f32_e32 v50, v53, v49
	v_cvt_pk_bf16_f32 v50, v50, s0
	v_mul_f32_e32 v56, v56, v49
	ds_write_b16 v249, v50 offset:128
	v_mul_f32_e32 v50, v52, v49
	v_cvt_pk_bf16_f32 v56, v56, s0
	v_cvt_pk_bf16_f32 v50, v50, s0
	ds_write_b16 v249, v56
	v_mul_f32_e32 v56, v64, v49
	v_mul_f32_e32 v51, v51, v49
	ds_write_b16 v249, v50 offset:160
	v_mul_f32_e32 v50, v55, v49
	v_mul_f32_e32 v52, v54, v49
	v_mul_f32_e32 v49, 0x4b800000, v48
	v_cmp_gt_f32_e64 s[74:75], s33, v48
	v_cvt_pk_bf16_f32 v51, v51, s0
	v_cvt_pk_bf16_f32 v50, v50, s0
	v_cndmask_b32_e64 v48, v48, v49, s[74:75]
	v_rsq_f32_e32 v53, v48
	v_pk_add_f32 v[48:49], v[76:77], 0 op_sel_hi:[1,0]
	ds_write_b16 v249, v51 offset:64
	v_pk_add_f32 v[48:49], v[48:49], v[80:81]
	ds_write_b16 v249, v50 offset:192
	v_pk_add_f32 v[48:49], v[48:49], v[84:85]
	v_cvt_pk_bf16_f32 v52, v52, s0
	v_pk_add_f32 v[48:49], v[48:49], v[88:89]
	ds_write_b16 v249, v52 offset:224
	v_pk_add_f32 v[48:49], v[48:49], v[92:93]
	v_mul_f32_e32 v52, 0x45800000, v53
	v_pk_add_f32 v[48:49], v[48:49], v[96:97]
	v_cndmask_b32_e64 v82, v53, v52, s[74:75]
	v_pk_add_f32 v[48:49], v[48:49], v[100:101]
	v_mul_f32_e32 v52, v57, v82
	v_pk_add_f32 v[48:49], v[48:49], v[44:45]
	ds_bpermute_b32 v50, v127, v48
	ds_bpermute_b32 v51, v127, v49
	v_cvt_pk_bf16_f32 v52, v52, s0
	ds_write_b16 v249, v52 offset:272
	v_mul_f32_e32 v52, v65, v82
	v_cvt_pk_bf16_f32 v83, v52, s0
	s_waitcnt lgkmcnt(1)
	v_pk_add_f32 v[48:49], v[48:49], v[50:51]
	ds_bpermute_b32 v50, v130, v48
	ds_bpermute_b32 v51, v130, v49
	v_mov_b32_e32 v52, v88
	v_mov_b32_e32 v53, v84
	v_mov_b32_e32 v84, v89
	v_mov_b32_e32 v54, v96
	s_waitcnt lgkmcnt(0)
	v_pk_add_f32 v[48:49], v[48:49], v[50:51]
	ds_bpermute_b32 v50, v131, v48
	ds_bpermute_b32 v51, v131, v49
	v_mov_b32_e32 v55, v92
	v_mov_b32_e32 v92, v97
	v_cvt_pk_bf16_f32 v56, v56, s0
	ds_write_b16 v249, v56 offset:32
	s_waitcnt lgkmcnt(1)
	v_pk_add_f32 v[48:49], v[48:49], v[50:51]
	ds_bpermute_b32 v50, v132, v48
	ds_bpermute_b32 v51, v132, v49
	v_mov_b32_e32 v56, v44
	v_mov_b32_e32 v57, v100
	v_mov_b32_e32 v100, v45
	v_mul_f32_e32 v47, v47, v82
	s_waitcnt lgkmcnt(0)
	v_pk_add_f32 v[48:49], v[48:49], v[50:51]
	v_cvt_pk_bf16_f32 v47, v47, s0
	v_pk_mul_f32 v[50:51], v[48:49], s[18:19] op_sel_hi:[1,0]
	v_pk_fma_f32 v[66:67], v[48:49], s[18:19], v[76:77] op_sel_hi:[1,0,1] neg_lo:[1,0,0] neg_hi:[1,0,0]
	v_pk_add_f32 v[52:53], v[52:53], v[50:51] op_sel_hi:[1,0] neg_lo:[0,1] neg_hi:[0,1]
	v_pk_fma_f32 v[48:49], v[48:49], s[18:19], v[80:81] op_sel_hi:[1,0,1] neg_lo:[1,0,0] neg_hi:[1,0,0]
	v_pk_add_f32 v[72:73], v[84:85], v[50:51] op_sel:[0,1] neg_lo:[0,1] neg_hi:[0,1]
	v_pk_mul_f32 v[60:61], v[52:53], v[52:53]
	v_pk_mul_f32 v[70:71], v[48:49], v[48:49]
	v_pk_mul_f32 v[74:75], v[72:73], v[72:73]
	v_pk_add_f32 v[54:55], v[54:55], v[50:51] op_sel_hi:[1,0] neg_lo:[0,1] neg_hi:[0,1]
	v_pk_fma_f32 v[70:71], v[66:67], v[66:67], v[70:71]
	v_pk_add_f32 v[76:77], v[92:93], v[50:51] op_sel:[0,1] neg_lo:[0,1] neg_hi:[0,1]
	v_mov_b32_e32 v81, v60
	v_mov_b32_e32 v60, v75
	v_pk_mul_f32 v[62:63], v[54:55], v[54:55]
	v_pk_mul_f32 v[78:79], v[76:77], v[76:77]
	v_mov_b32_e32 v80, v74
	v_pk_add_f32 v[60:61], v[60:61], v[70:71] op_sel:[0,1] op_sel_hi:[1,0]
	v_pk_add_f32 v[56:57], v[56:57], v[50:51] op_sel_hi:[1,0] neg_lo:[0,1] neg_hi:[0,1]
	v_pk_add_f32 v[44:45], v[100:101], v[50:51] op_sel:[0,1] neg_lo:[0,1] neg_hi:[0,1]
	v_pk_add_f32 v[60:61], v[80:81], v[60:61]
	v_mov_b32_e32 v70, v79
	v_mov_b32_e32 v71, v63
	v_pk_mul_f32 v[64:65], v[56:57], v[56:57]
	v_pk_mul_f32 v[50:51], v[44:45], v[44:45]
	v_pk_add_f32 v[60:61], v[70:71], v[60:61]
	v_mov_b32_e32 v79, v62
	v_pk_add_f32 v[60:61], v[78:79], v[60:61]
	v_mov_b32_e32 v62, v51
	v_mov_b32_e32 v63, v65
	v_pk_add_f32 v[60:61], v[62:63], v[60:61]
	v_mov_b32_e32 v51, v64
	v_pk_add_f32 v[50:51], v[50:51], v[60:61]
	ds_bpermute_b32 v61, v127, v51
	ds_bpermute_b32 v60, v127, v50
	v_mul_f32_e32 v62, v69, v82
	v_cvt_pk_bf16_f32 v62, v62, s0
	ds_write_b16 v249, v62 offset:336
	v_mul_f32_e32 v62, v68, v82
	s_waitcnt lgkmcnt(1)
	v_pk_add_f32 v[50:51], v[50:51], v[60:61]
	ds_bpermute_b32 v61, v130, v51
	ds_bpermute_b32 v60, v130, v50
	v_cvt_pk_bf16_f32 v62, v62, s0
	v_mul_f32_e32 v46, v46, v82
	ds_write_b16 v249, v62 offset:368
	ds_write_b16 v249, v47 offset:400
	s_waitcnt lgkmcnt(2)
	v_pk_add_f32 v[50:51], v[50:51], v[60:61]
	ds_bpermute_b32 v61, v131, v51
	ds_bpermute_b32 v60, v131, v50
	v_cvt_pk_bf16_f32 v62, v46, s0
	v_mul_f32_e32 v43, v43, v82
	v_cvt_pk_bf16_f32 v43, v43, s0
	ds_write_b16 v249, v43 offset:464
	s_waitcnt lgkmcnt(1)
	v_pk_add_f32 v[46:47], v[50:51], v[60:61]
	ds_bpermute_b32 v51, v132, v47
	ds_bpermute_b32 v50, v132, v46
	v_mul_f32_e32 v42, v42, v82
	v_cvt_pk_bf16_f32 v42, v42, s0
	ds_write_b16 v249, v42 offset:496
	ds_write_b16 v249, v83 offset:304
	s_waitcnt lgkmcnt(2)
; #define LAS __attribute__((address_space(3)))
; __device__ __forceinline__ unsigned pk2(float lo, float hi) { const f32x2_t v = {lo, hi}; const bf16v2_t b = __builtin_convertvector(v, bf16v2_t); return __builtin_bit_cast(unsigned, b); }
; __device__ __forceinline__ bf16_t f2bf(float f) { return (bf16_t)(pk2(f, 0.f) & 0xffffu); }
; __device__ __forceinline__ float bflo(unsigned u) { return __uint_as_float(u << 16); }
; __device__ __forceinline__ float bfhi(unsigned u) { return __uint_as_float(u & 0xffff0000u); }
; __device__ __forceinline__ void ret_out_phase(const Args& A, Frame& F, int l, bool lastl, bf16_t* ARET, bf16_t* ALRU) {
;     ...
;             for (int dvt = 0; dvt < 8; ++dvt) os[(16 * w + 4 * fq + r) * 136 + 16 * dvt + fr] = f2bf((O[dvt][r] - mu) * rstd);
;         }
;         __builtin_amdgcn_fence(__ATOMIC_RELEASE, "workgroup"); __builtin_amdgcn_wave_barrier(); __builtin_amdgcn_fence(__ATOMIC_ACQUIRE, "workgroup");
;         {
;             const int rr = 16 * w + (lane >> 2), cc = (lane & 3) * 32;
;             const size_t go = (rowbase + rr) * D + 128 * h + cc;
; #pragma unroll
;             for (int i = 0; i < 4; ++i) {
;                 const u32x4 ov = *(const LAS u32x4*)(os + rr * 136 + cc + 8 * i);
;                 const u32x4 gv = *(const u32x4*)(WSB(WS_SG) + go + 8 * i);
;                 u32x4 rv;
; #pragma unroll
;                 for (int e = 0; e < 4; ++e) rv[e] = pk2(bflo(ov[e]) * bflo(gv[e]), bfhi(ov[e]) * bfhi(gv[e]));
;                 *(u32x4*)(ARET + go + 8 * i) = rv;
;             }
;         }
; #pragma unroll
;         for (int i = 0; i < 4; ++i) {
;             const int u = tid + i * NTHREADS, r = u >> 4, c8 = (u & 15) * 8;
;             const size_t o = (rowbase + r) * D + 128 * h + c8;
;             const u32x4 hf = *(const u32x4*)(WSB(WS_HF) + o), hb = *(const u32x4*)(WSB(WS_HB) + o), gg = *(const u32x4*)(WSB(WS_GG) + o);
;             u32x4 ov;
; #pragma unroll
;             for (int e = 0; e < 4; ++e) ov[e] = pk2((bflo(hf[e]) + bflo(hb[e])) * bflo(gg[e]), (bfhi(hf[e]) + bfhi(hb[e])) * bfhi(gg[e]));
;             *(u32x4*)(ALRU + o) = ov;
	v_pk_add_f32 v[46:47], v[46:47], v[50:51]
	ds_write_b16 v249, v62 offset:432
	v_pk_fma_f32 v[46:47], v[46:47], s[18:19], v[58:59] op_sel_hi:[1,0,0]
	s_nop 0
	v_mul_f32_e32 v43, 0x4b800000, v47
	v_cmp_gt_f32_e64 s[74:75], s33, v47
	s_nop 1
	v_cndmask_b32_e64 v43, v47, v43, s[74:75]
	v_rsq_f32_e32 v43, v43
	s_nop 0
	v_mul_f32_e32 v42, 0x45800000, v43
	v_cndmask_b32_e64 v42, v43, v42, s[74:75]
	v_mul_f32_e32 v43, v66, v42
	v_cvt_pk_bf16_f32 v43, v43, s0
	ds_write_b16 v249, v43 offset:544
	v_mul_f32_e32 v43, v48, v42
	v_cvt_pk_bf16_f32 v43, v43, s0
	ds_write_b16 v249, v43 offset:576
	v_mul_f32_e32 v43, v53, v42
	v_cvt_pk_bf16_f32 v43, v43, s0
	ds_write_b16 v249, v43 offset:608
	v_mul_f32_e32 v43, v52, v42
	v_cvt_pk_bf16_f32 v43, v43, s0
	ds_write_b16 v249, v43 offset:640
	v_mul_f32_e32 v43, v55, v42
	v_cvt_pk_bf16_f32 v43, v43, s0
	ds_write_b16 v249, v43 offset:672
	v_mul_f32_e32 v43, v54, v42
	v_cvt_pk_bf16_f32 v43, v43, s0
	ds_write_b16 v249, v43 offset:704
	v_mul_f32_e32 v43, v57, v42
	v_cvt_pk_bf16_f32 v43, v43, s0
	ds_write_b16 v249, v43 offset:736
	v_mul_f32_e32 v43, 0x4b800000, v46
	v_cmp_gt_f32_e64 s[74:75], s33, v46
	v_mul_f32_e32 v42, v56, v42
	v_cvt_pk_bf16_f32 v42, v42, s0
	v_cndmask_b32_e64 v43, v46, v43, s[74:75]
	v_rsq_f32_e32 v43, v43
	ds_write_b16 v249, v42 offset:768
	v_mul_f32_e32 v42, 0x45800000, v43
	v_cndmask_b32_e64 v42, v43, v42, s[74:75]
	v_mul_f32_e32 v43, v67, v42
	v_cvt_pk_bf16_f32 v43, v43, s0
	ds_write_b16 v249, v43 offset:816
	v_mul_f32_e32 v43, v49, v42
	v_cvt_pk_bf16_f32 v43, v43, s0
	ds_write_b16 v249, v43 offset:848
	v_mul_f32_e32 v43, v73, v42
	v_cvt_pk_bf16_f32 v43, v43, s0
	ds_write_b16 v249, v43 offset:880
	v_mul_f32_e32 v43, v72, v42
	v_cvt_pk_bf16_f32 v43, v43, s0
	ds_write_b16 v249, v43 offset:912
	v_mul_f32_e32 v43, v77, v42
	v_cvt_pk_bf16_f32 v43, v43, s0
	ds_write_b16 v249, v43 offset:944
	v_mul_f32_e32 v43, v76, v42
	v_cvt_pk_bf16_f32 v43, v43, s0
	ds_write_b16 v249, v43 offset:976
	v_mul_f32_e32 v43, v45, v42
	v_mul_f32_e32 v42, v44, v42
	v_cvt_pk_bf16_f32 v43, v43, s0
	v_cvt_pk_bf16_f32 v42, v42, s0
	ds_write_b16 v249, v43 offset:1008
	ds_write_b16 v249, v42 offset:1040
	v_lshl_add_u64 v[42:43], s[8:9], 0, v[124:125]
	v_lshlrev_b64 v[42:43], 10, v[42:43]
	v_or_b32_e32 v42, v42, v126
	v_or_b32_e32 v42, s82, v42
	v_lshlrev_b64 v[54:55], 1, v[42:43]
	v_lshl_add_u64 v[42:43], s[50:51], 0, v[54:55]
	s_waitcnt lgkmcnt(0)
	v_add_u32_e32 v129, s8, v124
	v_lshlrev_b32_e32 v129, 11, v129
	v_or_b32_e32 v100, s82, v126
	v_lshl_or_b32 v129, v100, 1, v129
	v_or_b32_e32 v100, s82, v104
	v_add_u32_e32 v141, s8, v106
	v_lshlrev_b32_e32 v141, 11, v141
	v_lshl_or_b32 v141, v100, 1, v141
	v_add_u32_e32 v250, s8, v108
	v_lshlrev_b32_e32 v250, 11, v250
	v_lshl_or_b32 v250, v100, 1, v250
	v_add_u32_e32 v251, s8, v110
	v_lshlrev_b32_e32 v251, 11, v251
	v_lshl_or_b32 v251, v100, 1, v251
	v_add_u32_e32 v252, s8, v112
	v_lshlrev_b32_e32 v252, 11, v252
	v_lshl_or_b32 v252, v100, 1, v252
	global_load_dwordx4 v[56:59], v129, s[50:51]
	global_load_dwordx4 v[60:63], v129, s[50:51] offset:16
	global_load_dwordx4 v[64:67], v129, s[50:51] offset:32
	global_load_dwordx4 v[68:71], v129, s[50:51] offset:48
	global_load_dwordx4 v[72:75], v141, s[10:11]
	global_load_dwordx4 v[76:79], v141, s[12:13]
	global_load_dwordx4 v[80:83], v141, s[14:15]
	global_load_dwordx4 v[84:87], v250, s[10:11]
	global_load_dwordx4 v[88:91], v250, s[12:13]
	global_load_dwordx4 v[92:95], v250, s[14:15]
	ds_read_b128 v[96:99], v133
	ds_read_b128 v[44:47], v133 offset:16
	s_waitcnt vmcnt(9) lgkmcnt(1)
	v_lshlrev_b32_e32 v100, 16, v96
	v_and_b32_e32 v101, 0xffff0000, v96
	v_lshlrev_b32_e32 v52, 16, v56
	v_and_b32_e32 v53, 0xffff0000, v56
	v_pk_mul_f32 v[100:101], v[100:101], v[52:53]
	s_nop 0
	v_cvt_pk_bf16_f32 v56, v100, v101
	v_lshlrev_b32_e32 v100, 16, v97
	v_and_b32_e32 v101, 0xffff0000, v97
	v_lshlrev_b32_e32 v52, 16, v57
	v_and_b32_e32 v53, 0xffff0000, v57
	v_pk_mul_f32 v[100:101], v[100:101], v[52:53]
	s_nop 0
	v_cvt_pk_bf16_f32 v57, v100, v101
	v_lshlrev_b32_e32 v100, 16, v98
	v_and_b32_e32 v101, 0xffff0000, v98
	v_lshlrev_b32_e32 v52, 16, v58
	v_and_b32_e32 v53, 0xffff0000, v58
	v_pk_mul_f32 v[100:101], v[100:101], v[52:53]
	s_nop 0
	v_cvt_pk_bf16_f32 v58, v100, v101
	v_lshlrev_b32_e32 v100, 16, v99
	v_and_b32_e32 v101, 0xffff0000, v99
	v_lshlrev_b32_e32 v52, 16, v59
	v_and_b32_e32 v53, 0xffff0000, v59
	v_pk_mul_f32 v[100:101], v[100:101], v[52:53]
	s_nop 0
	v_cvt_pk_bf16_f32 v59, v100, v101
	global_store_dwordx4 v129, v[56:59], s[88:89]
	s_waitcnt vmcnt(9) lgkmcnt(0)
	v_lshlrev_b32_e32 v100, 16, v44
	v_and_b32_e32 v101, 0xffff0000, v44
	v_lshlrev_b32_e32 v52, 16, v60
	v_and_b32_e32 v53, 0xffff0000, v60
	v_pk_mul_f32 v[100:101], v[100:101], v[52:53]
	s_nop 0
	v_cvt_pk_bf16_f32 v60, v100, v101
	v_lshlrev_b32_e32 v100, 16, v45
	v_and_b32_e32 v101, 0xffff0000, v45
	v_lshlrev_b32_e32 v52, 16, v61
	v_and_b32_e32 v53, 0xffff0000, v61
	v_pk_mul_f32 v[100:101], v[100:101], v[52:53]
	s_nop 0
	v_cvt_pk_bf16_f32 v61, v100, v101
	v_lshlrev_b32_e32 v100, 16, v46
	v_and_b32_e32 v101, 0xffff0000, v46
	v_lshlrev_b32_e32 v52, 16, v62
	v_and_b32_e32 v53, 0xffff0000, v62
	v_pk_mul_f32 v[100:101], v[100:101], v[52:53]
	s_nop 0
	v_cvt_pk_bf16_f32 v62, v100, v101
	v_lshlrev_b32_e32 v100, 16, v47
	v_and_b32_e32 v101, 0xffff0000, v47
	v_lshlrev_b32_e32 v52, 16, v63
	v_and_b32_e32 v53, 0xffff0000, v63
	v_pk_mul_f32 v[100:101], v[100:101], v[52:53]
	s_nop 0
	v_cvt_pk_bf16_f32 v63, v100, v101
	global_store_dwordx4 v129, v[60:63], s[88:89] offset:16
	ds_read_b128 v[96:99], v133 offset:32
	ds_read_b128 v[44:47], v133 offset:48
	s_waitcnt vmcnt(9) lgkmcnt(1)
; #define LAS __attribute__((address_space(3)))
; __device__ __forceinline__ unsigned pk2(float lo, float hi) { const f32x2_t v = {lo, hi}; const bf16v2_t b = __builtin_convertvector(v, bf16v2_t); return __builtin_bit_cast(unsigned, b); }
; __device__ __forceinline__ float bflo(unsigned u) { return __uint_as_float(u << 16); }
; __device__ __forceinline__ float bfhi(unsigned u) { return __uint_as_float(u & 0xffff0000u); }
; __device__ __forceinline__ void ret_out_phase(const Args& A, Frame& F, int l, bool lastl, bf16_t* ARET, bf16_t* ALRU) {
;     ...
;         {
;             const int rr = 16 * w + (lane >> 2), cc = (lane & 3) * 32;
;             const size_t go = (rowbase + rr) * D + 128 * h + cc;
; #pragma unroll
;             for (int i = 0; i < 4; ++i) {
;                 const u32x4 ov = *(const LAS u32x4*)(os + rr * 136 + cc + 8 * i);
;                 const u32x4 gv = *(const u32x4*)(WSB(WS_SG) + go + 8 * i);
;                 u32x4 rv;
; #pragma unroll
;                 for (int e = 0; e < 4; ++e) rv[e] = pk2(bflo(ov[e]) * bflo(gv[e]), bfhi(ov[e]) * bfhi(gv[e]));
;                 *(u32x4*)(ARET + go + 8 * i) = rv;
;             }
;         }
; #pragma unroll
;         for (int i = 0; i < 4; ++i) {
;             const int u = tid + i * NTHREADS, r = u >> 4, c8 = (u & 15) * 8;
;             const size_t o = (rowbase + r) * D + 128 * h + c8;
;             const u32x4 hf = *(const u32x4*)(WSB(WS_HF) + o), hb = *(const u32x4*)(WSB(WS_HB) + o), gg = *(const u32x4*)(WSB(WS_GG) + o);
;             u32x4 ov;
; #pragma unroll
;             for (int e = 0; e < 4; ++e) ov[e] = pk2((bflo(hf[e]) + bflo(hb[e])) * bflo(gg[e]), (bfhi(hf[e]) + bfhi(hb[e])) * bfhi(gg[e]));
;             *(u32x4*)(ALRU + o) = ov;
	v_lshlrev_b32_e32 v100, 16, v96
	v_and_b32_e32 v101, 0xffff0000, v96
	v_lshlrev_b32_e32 v52, 16, v64
	v_and_b32_e32 v53, 0xffff0000, v64
	v_pk_mul_f32 v[100:101], v[100:101], v[52:53]
	s_nop 0
	v_cvt_pk_bf16_f32 v64, v100, v101
	v_lshlrev_b32_e32 v100, 16, v97
	v_and_b32_e32 v101, 0xffff0000, v97
	v_lshlrev_b32_e32 v52, 16, v65
	v_and_b32_e32 v53, 0xffff0000, v65
	v_pk_mul_f32 v[100:101], v[100:101], v[52:53]
	s_nop 0
	v_cvt_pk_bf16_f32 v65, v100, v101
	v_lshlrev_b32_e32 v100, 16, v98
	v_and_b32_e32 v101, 0xffff0000, v98
	v_lshlrev_b32_e32 v52, 16, v66
	v_and_b32_e32 v53, 0xffff0000, v66
	v_pk_mul_f32 v[100:101], v[100:101], v[52:53]
	s_nop 0
	v_cvt_pk_bf16_f32 v66, v100, v101
	v_lshlrev_b32_e32 v100, 16, v99
	v_and_b32_e32 v101, 0xffff0000, v99
	v_lshlrev_b32_e32 v52, 16, v67
	v_and_b32_e32 v53, 0xffff0000, v67
	v_pk_mul_f32 v[100:101], v[100:101], v[52:53]
	s_nop 0
	v_cvt_pk_bf16_f32 v67, v100, v101
	global_store_dwordx4 v129, v[64:67], s[88:89] offset:32
	s_waitcnt vmcnt(9) lgkmcnt(0)
	v_lshlrev_b32_e32 v100, 16, v44
	v_and_b32_e32 v101, 0xffff0000, v44
	v_lshlrev_b32_e32 v52, 16, v68
	v_and_b32_e32 v53, 0xffff0000, v68
	v_pk_mul_f32 v[100:101], v[100:101], v[52:53]
	s_nop 0
	v_cvt_pk_bf16_f32 v68, v100, v101
	v_lshlrev_b32_e32 v100, 16, v45
	v_and_b32_e32 v101, 0xffff0000, v45
	v_lshlrev_b32_e32 v52, 16, v69
	v_and_b32_e32 v53, 0xffff0000, v69
	v_pk_mul_f32 v[100:101], v[100:101], v[52:53]
	s_nop 0
	v_cvt_pk_bf16_f32 v69, v100, v101
	v_lshlrev_b32_e32 v100, 16, v46
	v_and_b32_e32 v101, 0xffff0000, v46
	v_lshlrev_b32_e32 v52, 16, v70
	v_and_b32_e32 v53, 0xffff0000, v70
	v_pk_mul_f32 v[100:101], v[100:101], v[52:53]
	s_nop 0
	v_cvt_pk_bf16_f32 v70, v100, v101
	v_lshlrev_b32_e32 v100, 16, v47
	v_and_b32_e32 v101, 0xffff0000, v47
	v_lshlrev_b32_e32 v52, 16, v71
	v_and_b32_e32 v53, 0xffff0000, v71
	v_pk_mul_f32 v[100:101], v[100:101], v[52:53]
	s_nop 0
	v_cvt_pk_bf16_f32 v71, v100, v101
	global_store_dwordx4 v129, v[68:71], s[88:89] offset:48
	s_nop 1
	global_load_dwordx4 v[56:59], v251, s[10:11]
	global_load_dwordx4 v[60:63], v251, s[12:13]
	global_load_dwordx4 v[64:67], v251, s[14:15]
	global_load_dwordx4 v[68:71], v252, s[10:11]
	global_load_dwordx4 v[44:47], v252, s[12:13]
	global_load_dwordx4 v[48:51], v252, s[14:15]
	s_waitcnt vmcnt(13)
	v_lshlrev_b32_e32 v100, 16, v72
	v_and_b32_e32 v101, 0xffff0000, v72
	v_lshlrev_b32_e32 v52, 16, v76
	v_and_b32_e32 v53, 0xffff0000, v76
	v_pk_add_f32 v[100:101], v[100:101], v[52:53]
	v_lshlrev_b32_e32 v52, 16, v80
	v_and_b32_e32 v53, 0xffff0000, v80
	v_pk_mul_f32 v[100:101], v[100:101], v[52:53]
	s_nop 0
	v_cvt_pk_bf16_f32 v72, v100, v101
	v_lshlrev_b32_e32 v100, 16, v73
	v_and_b32_e32 v101, 0xffff0000, v73
	v_lshlrev_b32_e32 v52, 16, v77
	v_and_b32_e32 v53, 0xffff0000, v77
	v_pk_add_f32 v[100:101], v[100:101], v[52:53]
	v_lshlrev_b32_e32 v52, 16, v81
	v_and_b32_e32 v53, 0xffff0000, v81
	v_pk_mul_f32 v[100:101], v[100:101], v[52:53]
	s_nop 0
	v_cvt_pk_bf16_f32 v73, v100, v101
	v_lshlrev_b32_e32 v100, 16, v74
	v_and_b32_e32 v101, 0xffff0000, v74
	v_lshlrev_b32_e32 v52, 16, v78
	v_and_b32_e32 v53, 0xffff0000, v78
	v_pk_add_f32 v[100:101], v[100:101], v[52:53]
	v_lshlrev_b32_e32 v52, 16, v82
	v_and_b32_e32 v53, 0xffff0000, v82
	v_pk_mul_f32 v[100:101], v[100:101], v[52:53]
	s_nop 0
	v_cvt_pk_bf16_f32 v74, v100, v101
	v_lshlrev_b32_e32 v100, 16, v75
	v_and_b32_e32 v101, 0xffff0000, v75
	v_lshlrev_b32_e32 v52, 16, v79
	v_and_b32_e32 v53, 0xffff0000, v79
	v_pk_add_f32 v[100:101], v[100:101], v[52:53]
	v_lshlrev_b32_e32 v52, 16, v83
	v_and_b32_e32 v53, 0xffff0000, v83
	v_pk_mul_f32 v[100:101], v[100:101], v[52:53]
	s_nop 0
	v_cvt_pk_bf16_f32 v75, v100, v101
	global_store_dwordx4 v141, v[72:75], s[90:91]
	s_waitcnt vmcnt(11)
; __device__ __forceinline__ unsigned pk2(float lo, float hi) { const f32x2_t v = {lo, hi}; const bf16v2_t b = __builtin_convertvector(v, bf16v2_t); return __builtin_bit_cast(unsigned, b); }
; __device__ __forceinline__ float bflo(unsigned u) { return __uint_as_float(u << 16); }
; __device__ __forceinline__ float bfhi(unsigned u) { return __uint_as_float(u & 0xffff0000u); }
; __device__ __forceinline__ void ret_out_phase(const Args& A, Frame& F, int l, bool lastl, bf16_t* ARET, bf16_t* ALRU) {
;     ...
; #pragma unroll
;         for (int i = 0; i < 4; ++i) {
;             const int u = tid + i * NTHREADS, r = u >> 4, c8 = (u & 15) * 8;
;             const size_t o = (rowbase + r) * D + 128 * h + c8;
;             const u32x4 hf = *(const u32x4*)(WSB(WS_HF) + o), hb = *(const u32x4*)(WSB(WS_HB) + o), gg = *(const u32x4*)(WSB(WS_GG) + o);
;             u32x4 ov;
; #pragma unroll
;             for (int e = 0; e < 4; ++e) ov[e] = pk2((bflo(hf[e]) + bflo(hb[e])) * bflo(gg[e]), (bfhi(hf[e]) + bfhi(hb[e])) * bfhi(gg[e]));
;             *(u32x4*)(ALRU + o) = ov;
;         }
	v_lshlrev_b32_e32 v100, 16, v84
	v_and_b32_e32 v101, 0xffff0000, v84
	v_lshlrev_b32_e32 v52, 16, v88
	v_and_b32_e32 v53, 0xffff0000, v88
	v_pk_add_f32 v[100:101], v[100:101], v[52:53]
	v_lshlrev_b32_e32 v52, 16, v92
	v_and_b32_e32 v53, 0xffff0000, v92
	v_pk_mul_f32 v[100:101], v[100:101], v[52:53]
	s_nop 0
	v_cvt_pk_bf16_f32 v84, v100, v101
	v_lshlrev_b32_e32 v100, 16, v85
	v_and_b32_e32 v101, 0xffff0000, v85
	v_lshlrev_b32_e32 v52, 16, v89
	v_and_b32_e32 v53, 0xffff0000, v89
	v_pk_add_f32 v[100:101], v[100:101], v[52:53]
	v_lshlrev_b32_e32 v52, 16, v93
	v_and_b32_e32 v53, 0xffff0000, v93
	v_pk_mul_f32 v[100:101], v[100:101], v[52:53]
	s_nop 0
	v_cvt_pk_bf16_f32 v85, v100, v101
	v_lshlrev_b32_e32 v100, 16, v86
	v_and_b32_e32 v101, 0xffff0000, v86
	v_lshlrev_b32_e32 v52, 16, v90
	v_and_b32_e32 v53, 0xffff0000, v90
	v_pk_add_f32 v[100:101], v[100:101], v[52:53]
	v_lshlrev_b32_e32 v52, 16, v94
	v_and_b32_e32 v53, 0xffff0000, v94
	v_pk_mul_f32 v[100:101], v[100:101], v[52:53]
	s_nop 0
	v_cvt_pk_bf16_f32 v86, v100, v101
	v_lshlrev_b32_e32 v100, 16, v87
	v_and_b32_e32 v101, 0xffff0000, v87
	v_lshlrev_b32_e32 v52, 16, v91
	v_and_b32_e32 v53, 0xffff0000, v91
	v_pk_add_f32 v[100:101], v[100:101], v[52:53]
	v_lshlrev_b32_e32 v52, 16, v95
	v_and_b32_e32 v53, 0xffff0000, v95
	v_pk_mul_f32 v[100:101], v[100:101], v[52:53]
	s_nop 0
	v_cvt_pk_bf16_f32 v87, v100, v101
	global_store_dwordx4 v250, v[84:87], s[90:91]
	s_waitcnt vmcnt(5)
	v_lshlrev_b32_e32 v100, 16, v56
	v_and_b32_e32 v101, 0xffff0000, v56
	v_lshlrev_b32_e32 v52, 16, v60
	v_and_b32_e32 v53, 0xffff0000, v60
	v_pk_add_f32 v[100:101], v[100:101], v[52:53]
	v_lshlrev_b32_e32 v52, 16, v64
	v_and_b32_e32 v53, 0xffff0000, v64
	v_pk_mul_f32 v[100:101], v[100:101], v[52:53]
	s_nop 0
	v_cvt_pk_bf16_f32 v56, v100, v101
	v_lshlrev_b32_e32 v100, 16, v57
	v_and_b32_e32 v101, 0xffff0000, v57
	v_lshlrev_b32_e32 v52, 16, v61
	v_and_b32_e32 v53, 0xffff0000, v61
	v_pk_add_f32 v[100:101], v[100:101], v[52:53]
	v_lshlrev_b32_e32 v52, 16, v65
	v_and_b32_e32 v53, 0xffff0000, v65
	v_pk_mul_f32 v[100:101], v[100:101], v[52:53]
	s_nop 0
	v_cvt_pk_bf16_f32 v57, v100, v101
	v_lshlrev_b32_e32 v100, 16, v58
	v_and_b32_e32 v101, 0xffff0000, v58
	v_lshlrev_b32_e32 v52, 16, v62
	v_and_b32_e32 v53, 0xffff0000, v62
	v_pk_add_f32 v[100:101], v[100:101], v[52:53]
	v_lshlrev_b32_e32 v52, 16, v66
	v_and_b32_e32 v53, 0xffff0000, v66
	v_pk_mul_f32 v[100:101], v[100:101], v[52:53]
	s_nop 0
	v_cvt_pk_bf16_f32 v58, v100, v101
	v_lshlrev_b32_e32 v100, 16, v59
	v_and_b32_e32 v101, 0xffff0000, v59
	v_lshlrev_b32_e32 v52, 16, v63
	v_and_b32_e32 v53, 0xffff0000, v63
	v_pk_add_f32 v[100:101], v[100:101], v[52:53]
	v_lshlrev_b32_e32 v52, 16, v67
	v_and_b32_e32 v53, 0xffff0000, v67
	v_pk_mul_f32 v[100:101], v[100:101], v[52:53]
	s_nop 0
	v_cvt_pk_bf16_f32 v59, v100, v101
	global_store_dwordx4 v251, v[56:59], s[90:91]
	s_waitcnt vmcnt(3)
	v_lshlrev_b32_e32 v100, 16, v68
	v_and_b32_e32 v101, 0xffff0000, v68
	v_lshlrev_b32_e32 v52, 16, v44
	v_and_b32_e32 v53, 0xffff0000, v44
	v_pk_add_f32 v[100:101], v[100:101], v[52:53]
	v_lshlrev_b32_e32 v52, 16, v48
	v_and_b32_e32 v53, 0xffff0000, v48
	v_pk_mul_f32 v[100:101], v[100:101], v[52:53]
	s_nop 0
	v_cvt_pk_bf16_f32 v68, v100, v101
	v_lshlrev_b32_e32 v100, 16, v69
	v_and_b32_e32 v101, 0xffff0000, v69
	v_lshlrev_b32_e32 v52, 16, v45
	v_and_b32_e32 v53, 0xffff0000, v45
	v_pk_add_f32 v[100:101], v[100:101], v[52:53]
	v_lshlrev_b32_e32 v52, 16, v49
	v_and_b32_e32 v53, 0xffff0000, v49
	v_pk_mul_f32 v[100:101], v[100:101], v[52:53]
	s_nop 0
	v_cvt_pk_bf16_f32 v69, v100, v101
	v_lshlrev_b32_e32 v100, 16, v70
	v_and_b32_e32 v101, 0xffff0000, v70
	v_lshlrev_b32_e32 v52, 16, v46
	v_and_b32_e32 v53, 0xffff0000, v46
	v_pk_add_f32 v[100:101], v[100:101], v[52:53]
	v_lshlrev_b32_e32 v52, 16, v50
	v_and_b32_e32 v53, 0xffff0000, v50
	v_pk_mul_f32 v[100:101], v[100:101], v[52:53]
	s_nop 0
	v_cvt_pk_bf16_f32 v70, v100, v101
	v_lshlrev_b32_e32 v100, 16, v71
	v_and_b32_e32 v101, 0xffff0000, v71
	v_lshlrev_b32_e32 v52, 16, v47
	v_and_b32_e32 v53, 0xffff0000, v47
	v_pk_add_f32 v[100:101], v[100:101], v[52:53]
	v_lshlrev_b32_e32 v52, 16, v51
	v_and_b32_e32 v53, 0xffff0000, v51
	v_pk_mul_f32 v[100:101], v[100:101], v[52:53]
	s_nop 0
	v_cvt_pk_bf16_f32 v71, v100, v101
	global_store_dwordx4 v252, v[68:71], s[90:91]
	s_cbranch_scc1 .LBB0_30

; __device__ __forceinline__ unsigned pk2(float lo, float hi) { const f32x2_t v = {lo, hi}; const bf16v2_t b = __builtin_convertvector(v, bf16v2_t); return __builtin_bit_cast(unsigned, b); }
; __device__ __forceinline__ void norm_phase(const Args& A, Frame& F, int l, int s, bool latonly, bool tailsum) {
;     ...
;         { const int rn = row + stride < MROWS ? row + stride : row;
;           const u32x2* xrn = (const u32x2*)(WSB(WS_R) + (size_t)rn * D) + F.lane;
; #pragma unroll
;           for (int j = 0; j < 4; ++j) nx[j] = xrn[64 * j]; }
;     ...
;         const float* mp = WSF(WS_MODS) + (size_t)(l * 9 + mr) * NMOD + (size_t)(3 * s) * D;
;         u32x2* o8 = (u32x2*)(WSB(WS_AN) + (size_t)row * D) + F.lane;
; #pragma unroll
;         for (int j = 0; j < 4; ++j) {
;             const int col = 4 * (F.lane + 64 * j);
;             const f32x4 gv = gvh[j], sh = *(const f32x4*)(mp + col), sc = *(const f32x4*)(mp + D + col);
;             const f32x4 y = (v[j] * rstd * gv) * (sc + 1.f) + sh;
;             u32x2 o; o.x = pk2(y[0], y[1]); o.y = pk2(y[2], y[3]);
;             o8[64 * j] = o;
;         }
.LBB0_693:
	s_and_b64 s[40:41], s[40:41], exec
	s_cselect_b32 s4, 8, s4
	s_add_i32 s4, s4, s29
	s_mul_hi_i32 s5, s4, 0x9000
	s_mul_i32 s4, s4, 0x9000
	s_add_u32 s4, s2, s4
	s_addc_u32 s5, s20, s5
	s_add_u32 s40, s4, 0x1000
	s_addc_u32 s41, s5, 0
	global_load_dwordx4 v[192:195], v0, s[40:41]
	global_load_dwordx4 v[196:199], v0, s[4:5]
	global_load_dwordx4 v[200:203], v103, s[40:41]
	global_load_dwordx4 v[204:207], v0, s[4:5] offset:1024
	global_load_dwordx4 v[208:211], v112, s[40:41]
	global_load_dwordx4 v[212:215], v0, s[4:5] offset:2048
	global_load_dwordx4 v[216:219], v113, s[40:41]
	global_load_dwordx4 v[220:223], v0, s[4:5] offset:3072
	s_cmpk_lt_i32 s7, 0x4800
	s_cselect_b32 s4, s7, s48
	s_ashr_i32 s5, s4, 31
	s_lshl_b64 s[4:5], s[4:5], 11
	v_lshl_add_u64 v[24:25], v[18:19], 0, s[4:5]
	global_load_dwordx2 v[30:31], v[24:25], off
	global_load_dwordx2 v[28:29], v[24:25], off offset:512
	global_load_dwordx2 v[26:27], v[24:25], off offset:1024
	s_nop 0
	global_load_dwordx2 v[24:25], v[24:25], off offset:1536
	v_pk_mul_f32 v[56:57], v[40:41], v[40:41]
	v_pk_mul_f32 v[58:59], v[42:43], v[42:43]
	v_pk_mul_f32 v[60:61], v[44:45], v[44:45]
	v_pk_mul_f32 v[62:63], v[46:47], v[46:47]
	v_cmp_lt_i32_e32 vcc, v176, v175
	v_pk_mov_b32 v[68:69], v[62:63], v[60:61] op_sel:[1,0]
	v_mov_b32_e32 v63, v61
	v_pk_mov_b32 v[60:61], v[58:59], v[56:57] op_sel:[1,0]
	v_mov_b32_e32 v59, v57
	v_mul_f32_e32 v64, v38, v38
	v_mul_f32_e32 v66, v36, v36
	v_cndmask_b32_e32 v67, v174, v176, vcc
	v_pk_add_f32 v[62:63], v[68:69], v[62:63]
	v_pk_add_f32 v[58:59], v[60:61], v[58:59]
	v_pk_fma_f32 v[56:57], v[38:39], v[38:39], v[64:65] op_sel_hi:[1,1,0]
	v_pk_fma_f32 v[64:65], v[36:37], v[36:37], v[66:67] op_sel_hi:[1,1,0]
	v_pk_add_f32 v[60:61], v[62:63], v[62:63] op_sel_hi:[0,1]
	v_pk_add_f32 v[58:59], v[58:59], v[58:59] op_sel_hi:[0,1]
	v_mul_f32_e32 v56, v34, v34
	v_mul_f32_e32 v64, v35, v35
	v_mul_f32_e32 v60, v32, v32
	v_mul_f32_e32 v58, v33, v33
	v_pk_add_f32 v[56:57], v[56:57], v[64:65]
	v_pk_add_f32 v[58:59], v[60:61], v[58:59]
	v_lshlrev_b32_e32 v66, 2, v67
	v_pk_add_f32 v[56:57], v[56:57], v[58:59]
	v_cmp_lt_i32_e32 vcc, v177, v175
	v_add_f32_e32 v56, v56, v57
	ds_bpermute_b32 v57, v66, v56
	v_cndmask_b32_e32 v58, v174, v177, vcc
	v_lshlrev_b32_e32 v58, 2, v58
	v_cmp_lt_i32_e32 vcc, v178, v175
	s_waitcnt lgkmcnt(0)
	v_add_f32_e32 v56, v56, v57
	ds_bpermute_b32 v57, v58, v56
	v_cndmask_b32_e32 v58, v174, v178, vcc
	v_lshlrev_b32_e32 v58, 2, v58
	v_cmp_lt_i32_e32 vcc, v179, v175
	s_waitcnt lgkmcnt(0)
	v_add_f32_e32 v56, v56, v57
	ds_bpermute_b32 v57, v58, v56
	v_cndmask_b32_e32 v58, v174, v179, vcc
	v_lshlrev_b32_e32 v58, 2, v58
	v_cmp_lt_i32_e32 vcc, v180, v175
	s_waitcnt lgkmcnt(0)
	v_add_f32_e32 v56, v56, v57
	ds_bpermute_b32 v57, v58, v56
	v_cndmask_b32_e32 v58, v174, v180, vcc
	v_lshlrev_b32_e32 v58, 2, v58
	v_cmp_lt_i32_e32 vcc, v181, v175
	s_waitcnt lgkmcnt(0)
	v_add_f32_e32 v56, v56, v57
	ds_bpermute_b32 v57, v58, v56
	v_cndmask_b32_e32 v58, v174, v181, vcc
	v_lshlrev_b32_e32 v58, 2, v58
	s_waitcnt lgkmcnt(0)
	v_add_f32_e32 v56, v56, v57
	ds_bpermute_b32 v57, v58, v56
	s_waitcnt lgkmcnt(0)
	v_add_f32_e32 v56, v56, v57
	v_fmamk_f32 v56, v56, 0x3a800000, v170
	v_mul_f32_e32 v57, 0x4b800000, v56
	v_cmp_gt_f32_e32 vcc, s33, v56
	v_pk_mul_f32 v[58:59], v[2:3], v[2:3]
	v_pk_mul_f32 v[60:61], v[4:5], v[4:5]
	v_cndmask_b32_e32 v56, v56, v57, vcc
	v_rsq_f32_e32 v56, v56
	s_nop 0
	v_mul_f32_e32 v57, 0x45800000, v56
	v_cndmask_b32_e32 v56, v56, v57, vcc
	v_pk_mul_f32 v[44:45], v[44:45], v[56:57] op_sel_hi:[1,0]
	v_pk_mul_f32 v[46:47], v[46:47], v[56:57] op_sel_hi:[1,0]
	v_pk_mul_f32 v[44:45], v[4:5], v[44:45]
	v_pk_mul_f32 v[46:47], v[2:3], v[46:47]
	v_pk_mul_f32 v[40:41], v[40:41], v[56:57] op_sel_hi:[1,0]
	v_pk_mul_f32 v[42:43], v[42:43], v[56:57] op_sel_hi:[1,0]
	v_pk_mul_f32 v[40:41], v[8:9], v[40:41]
	v_pk_mul_f32 v[42:43], v[6:7], v[42:43]
	v_pk_mul_f32 v[36:37], v[36:37], v[56:57] op_sel_hi:[1,0]
	v_pk_mul_f32 v[38:39], v[38:39], v[56:57] op_sel_hi:[1,0]
	v_pk_mul_f32 v[36:37], v[12:13], v[36:37]
	v_pk_mul_f32 v[38:39], v[10:11], v[38:39]
	v_pk_mul_f32 v[32:33], v[32:33], v[56:57] op_sel_hi:[1,0]
	v_pk_mul_f32 v[34:35], v[34:35], v[56:57] op_sel_hi:[1,0]
	v_pk_mul_f32 v[32:33], v[16:17], v[32:33]
	v_pk_mul_f32 v[34:35], v[14:15], v[34:35]
	s_waitcnt vmcnt(4)
	v_pk_add_f32 v[194:195], v[194:195], 1.0 op_sel_hi:[1,0]
	v_pk_add_f32 v[192:193], v[192:193], 1.0 op_sel_hi:[1,0]
	v_pk_fma_f32 v[44:45], v[194:195], v[44:45], v[198:199]
	v_pk_fma_f32 v[46:47], v[192:193], v[46:47], v[196:197]
	s_nop 0
	v_cvt_pk_bf16_f32 v46, v46, v47
	v_cvt_pk_bf16_f32 v47, v44, v45
	global_store_dwordx2 v[22:23], v[46:47], off offset:-1024
	v_pk_add_f32 v[202:203], v[202:203], 1.0 op_sel_hi:[1,0]
	v_pk_add_f32 v[200:201], v[200:201], 1.0 op_sel_hi:[1,0]
	v_pk_fma_f32 v[40:41], v[202:203], v[40:41], v[206:207]
	v_pk_fma_f32 v[42:43], v[200:201], v[42:43], v[204:205]
	s_nop 0
	v_cvt_pk_bf16_f32 v42, v42, v43
	v_cvt_pk_bf16_f32 v43, v40, v41
	global_store_dwordx2 v[22:23], v[42:43], off offset:-512
	v_pk_add_f32 v[210:211], v[210:211], 1.0 op_sel_hi:[1,0]
	v_pk_add_f32 v[208:209], v[208:209], 1.0 op_sel_hi:[1,0]
	v_pk_fma_f32 v[36:37], v[210:211], v[36:37], v[214:215]
	v_pk_fma_f32 v[38:39], v[208:209], v[38:39], v[212:213]
	s_nop 0
	v_cvt_pk_bf16_f32 v38, v38, v39
	v_cvt_pk_bf16_f32 v39, v36, v37
	global_store_dwordx2 v[22:23], v[38:39], off
	v_pk_add_f32 v[218:219], v[218:219], 1.0 op_sel_hi:[1,0]
	v_pk_add_f32 v[216:217], v[216:217], 1.0 op_sel_hi:[1,0]
	v_pk_fma_f32 v[32:33], v[218:219], v[32:33], v[222:223]
	v_pk_fma_f32 v[34:35], v[216:217], v[34:35], v[220:221]
	s_nop 0
	v_cvt_pk_bf16_f32 v34, v34, v35
	v_cvt_pk_bf16_f32 v35, v32, v33
	global_store_dwordx2 v[22:23], v[34:35], off offset:512
	v_lshl_add_u64 v[22:23], v[22:23], 0, s[10:11]
	s_and_b64 vcc, exec, s[14:15]
	s_mov_b32 s48, s7
	s_waitcnt vmcnt(4)
	v_mov_b32_e32 v38, v30
	v_mov_b32_e32 v39, v31
	v_mov_b32_e32 v36, v28
	v_mov_b32_e32 v37, v29
	v_mov_b32_e32 v34, v26
	v_mov_b32_e32 v35, v27
	v_mov_b32_e32 v32, v24
	v_mov_b32_e32 v33, v25
	s_cbranch_vccnz .LBB0_698
	s_branch .LBB0_695
; __device__ __forceinline__ float bflo(unsigned u) { return __uint_as_float(u << 16); }
; __device__ __forceinline__ float bfhi(unsigned u) { return __uint_as_float(u & 0xffff0000u); }
; __device__ __forceinline__ void norm_phase(const Args& A, Frame& F, int l, int s, bool latonly, bool tailsum) {
;     ...
;     for (; row < MROWS; row += stride) {
;         u32x2 cx[4];
; #pragma unroll
;         for (int j = 0; j < 4; ++j) cx[j] = nx[j];
;         { const int rn = row + stride < MROWS ? row + stride : row;
;           const u32x2* xrn = (const u32x2*)(WSB(WS_R) + (size_t)rn * D) + F.lane;
; #pragma unroll
;           for (int j = 0; j < 4; ++j) nx[j] = xrn[64 * j]; }
;         const int b = row / TB, p = row - b * TB, mr = p < CTXL ? 8 : b;
;         if (latonly && p < CTXL) continue;
;         f32x4 v[4]; float ss = 0.f;
; #pragma unroll
;         for (int j = 0; j < 4; ++j) { const u32x2 xv = cx[j]; v[j][0] = bflo(xv.x); v[j][1] = bfhi(xv.x); v[j][2] = bflo(xv.y); v[j][3] = bfhi(xv.y); }
;         if (tailsum && row >= 16384) {
; #pragma unroll
;             for (int sp = 0; sp < 8; ++sp) {
;                 const u32x2* pr = (const u32x2*)(WSB(WS_PART) + ((size_t)sp * 2048 + (row - 16384)) * D) + F.lane;
; #pragma unroll
;                 for (int j = 0; j < 4; ++j) { const u32x2 pv = pr[64 * j]; v[j][0] += bflo(pv.x); v[j][1] += bfhi(pv.x); v[j][2] += bflo(pv.y); v[j][3] += bfhi(pv.y); }
;             }
.LBB0_694:
	s_cmpk_lt_i32 s7, 0x4800
	s_cselect_b32 s4, s7, s48
	s_ashr_i32 s5, s4, 31
	s_lshl_b64 s[4:5], s[4:5], 11
	v_lshl_add_u64 v[24:25], v[18:19], 0, s[4:5]
	global_load_dwordx2 v[30:31], v[24:25], off
	global_load_dwordx2 v[28:29], v[24:25], off offset:512
	global_load_dwordx2 v[26:27], v[24:25], off offset:1024
	s_nop 0
	global_load_dwordx2 v[24:25], v[24:25], off offset:1536
	v_lshl_add_u64 v[22:23], v[22:23], 0, s[10:11]
	s_and_b64 vcc, exec, s[14:15]
	s_mov_b32 s48, s7
	s_waitcnt vmcnt(3)
	v_mov_b32_e32 v38, v30
	v_mov_b32_e32 v39, v31
	s_waitcnt vmcnt(2)
	v_mov_b32_e32 v36, v28
	v_mov_b32_e32 v37, v29
	s_waitcnt vmcnt(1)
	v_mov_b32_e32 v34, v26
	v_mov_b32_e32 v35, v27
	s_waitcnt vmcnt(0)
	v_mov_b32_e32 v32, v24
	v_mov_b32_e32 v33, v25
	s_cbranch_vccnz .LBB0_698
.LBB0_695:
	s_add_i32 s7, s48, s6
	s_cmpk_gt_i32 s7, 0x47ff
	s_cselect_b64 s[14:15], -1, 0
	s_mul_hi_i32 s4, s48, 0x38e38e39
	s_lshr_b32 s5, s4, 31
	s_ashr_i32 s4, s4, 9
	s_add_i32 s4, s4, s5
	s_mul_i32 s5, s4, 0xfffff700
	s_add_i32 s5, s48, s5
	s_cmpk_lt_i32 s5, 0x100
	s_cselect_b64 s[40:41], -1, 0
	s_and_b64 s[42:43], s[8:9], s[40:41]
	s_and_b64 vcc, exec, s[42:43]
	s_cbranch_vccnz .LBB0_694
	s_cmpk_lt_i32 s48, 0x4000
	s_cselect_b64 s[42:43], -1, 0
	s_or_b64 s[42:43], s[12:13], s[42:43]
	v_lshlrev_b32_e32 v46, 16, v38
	v_and_b32_e32 v47, 0xffff0000, v38
	v_lshlrev_b32_e32 v44, 16, v39
	v_and_b32_e32 v45, 0xffff0000, v39
	v_lshlrev_b32_e32 v42, 16, v36
	v_and_b32_e32 v43, 0xffff0000, v36
	v_lshlrev_b32_e32 v40, 16, v37
	v_and_b32_e32 v41, 0xffff0000, v37
	v_lshlrev_b32_e32 v38, 16, v34
	v_and_b32_e32 v39, 0xffff0000, v34
	v_lshlrev_b32_e32 v36, 16, v35
	v_and_b32_e32 v37, 0xffff0000, v35
	v_lshlrev_b32_e32 v34, 16, v32
	v_and_b32_e32 v35, 0xffff0000, v32
	v_lshlrev_b32_e32 v32, 16, v33
	v_and_b32_e32 v33, 0xffff0000, v33
	s_and_b64 vcc, exec, s[42:43]
	s_cbranch_vccnz .LBB0_693
	s_add_i32 s82, s48, 0xffffc000
	s_lshl_b64 s[42:43], s[82:83], 11
	v_lshl_add_u64 v[48:49], v[20:21], 0, s[42:43]
	v_add_co_u32_e32 v50, vcc, 0x400000, v48
	global_load_dwordx2 v[68:69], v[48:49], off
	s_nop 0
	v_addc_co_u32_e32 v51, vcc, 0, v49, vcc
	v_add_co_u32_e32 v60, vcc, s33, v48
	global_load_dwordx2 v[70:71], v[50:51], off
	s_nop 0
	v_addc_co_u32_e32 v61, vcc, 0, v49, vcc
	v_add_co_u32_e32 v62, vcc, s25, v48
	global_load_dwordx2 v[72:73], v[60:61], off
	s_nop 0
	v_addc_co_u32_e32 v63, vcc, 0, v49, vcc
	v_add_co_u32_e32 v64, vcc, s27, v48
	global_load_dwordx2 v[86:87], v[62:63], off
	s_nop 0
	v_addc_co_u32_e32 v65, vcc, 0, v49, vcc
	v_add_co_u32_e32 v98, vcc, s28, v48
	global_load_dwordx2 v[90:91], v[64:65], off
	s_nop 0
	v_addc_co_u32_e32 v99, vcc, 0, v49, vcc
	v_add_co_u32_e32 v114, vcc, s35, v48
	global_load_dwordx2 v[92:93], v[98:99], off
	s_nop 0
	v_addc_co_u32_e32 v115, vcc, 0, v49, vcc
	global_load_dwordx2 v[94:95], v[114:115], off
	v_add_co_u32_e32 v108, vcc, s37, v48
	s_mov_b32 s49, s83
	s_nop 0
	v_addc_co_u32_e32 v109, vcc, 0, v49, vcc
	global_load_dwordx2 v[96:97], v[108:109], off
	global_load_dwordx2 v[88:89], v[48:49], off offset:512
	global_load_dwordx2 v[84:85], v[50:51], off offset:512
	global_load_dwordx2 v[82:83], v[60:61], off offset:512
	global_load_dwordx2 v[80:81], v[62:63], off offset:512
	global_load_dwordx2 v[74:75], v[64:65], off offset:512
	global_load_dwordx2 v[54:55], v[48:49], off offset:1024
	global_load_dwordx2 v[52:53], v[48:49], off offset:1536
	global_load_dwordx2 v[76:77], v[98:99], off offset:512
	global_load_dwordx2 v[56:57], v[50:51], off offset:1024
	s_nop 0
	global_load_dwordx2 v[50:51], v[50:51], off offset:1536
	s_nop 0
	global_load_dwordx2 v[78:79], v[114:115], off offset:512
	global_load_dwordx2 v[58:59], v[60:61], off offset:1024
	global_load_dwordx2 v[48:49], v[60:61], off offset:1536
	global_load_dwordx2 v[110:111], v[108:109], off offset:512
	global_load_dwordx2 v[106:107], v[62:63], off offset:1024
	global_load_dwordx2 v[66:67], v[62:63], off offset:1536
	global_load_dwordx2 v[104:105], v[64:65], off offset:1024
	s_nop 0
	global_load_dwordx2 v[64:65], v[64:65], off offset:1536
	s_nop 0
	global_load_dwordx2 v[100:101], v[98:99], off offset:1024
	global_load_dwordx2 v[62:63], v[98:99], off offset:1536
	s_nop 0
	global_load_dwordx2 v[98:99], v[114:115], off offset:1024
	global_load_dwordx2 v[60:61], v[114:115], off offset:1536
	s_nop 0
	global_load_dwordx2 v[114:115], v[108:109], off offset:1024
	s_nop 0
	global_load_dwordx2 v[108:109], v[108:109], off offset:1536
	s_lshl_b64 s[42:43], s[48:49], 11
	s_waitcnt vmcnt(31)
	v_lshlrev_b32_e32 v116, 16, v68
	v_and_b32_e32 v117, 0xffff0000, v68
	v_lshlrev_b32_e32 v68, 16, v69
	v_and_b32_e32 v69, 0xffff0000, v69
	v_pk_add_f32 v[44:45], v[44:45], v[68:69]
	s_waitcnt vmcnt(30)
	v_lshlrev_b32_e32 v68, 16, v71
	v_and_b32_e32 v69, 0xffff0000, v71
	v_pk_add_f32 v[44:45], v[44:45], v[68:69]
	v_pk_add_f32 v[46:47], v[46:47], v[116:117]
	v_lshlrev_b32_e32 v116, 16, v70
	s_waitcnt vmcnt(29)
	v_lshlrev_b32_e32 v68, 16, v73
	v_and_b32_e32 v69, 0xffff0000, v73
	v_pk_add_f32 v[44:45], v[44:45], v[68:69]
	v_and_b32_e32 v117, 0xffff0000, v70
	v_pk_add_f32 v[46:47], v[46:47], v[116:117]
	s_waitcnt vmcnt(28)
	v_lshlrev_b32_e32 v68, 16, v87
	v_and_b32_e32 v69, 0xffff0000, v87
	v_pk_add_f32 v[44:45], v[44:45], v[68:69]
	v_lshlrev_b32_e32 v116, 16, v72
	v_and_b32_e32 v117, 0xffff0000, v72
	s_waitcnt vmcnt(27)
	v_lshlrev_b32_e32 v68, 16, v91
	v_and_b32_e32 v69, 0xffff0000, v91
	v_pk_add_f32 v[44:45], v[44:45], v[68:69]
	v_pk_add_f32 v[46:47], v[46:47], v[116:117]
	v_lshlrev_b32_e32 v116, 16, v86
	s_waitcnt vmcnt(26)
	v_lshlrev_b32_e32 v68, 16, v93
	v_and_b32_e32 v69, 0xffff0000, v93
	v_pk_add_f32 v[44:45], v[44:45], v[68:69]
	s_waitcnt vmcnt(25)
; __device__ __forceinline__ float bflo(unsigned u) { return __uint_as_float(u << 16); }
; __device__ __forceinline__ float bfhi(unsigned u) { return __uint_as_float(u & 0xffff0000u); }
; __device__ __forceinline__ void norm_phase(const Args& A, Frame& F, int l, int s, bool latonly, bool tailsum) {
;     ...
;         if (tailsum && row >= 16384) {
; #pragma unroll
;             for (int sp = 0; sp < 8; ++sp) {
;                 const u32x2* pr = (const u32x2*)(WSB(WS_PART) + ((size_t)sp * 2048 + (row - 16384)) * D) + F.lane;
; #pragma unroll
;                 for (int j = 0; j < 4; ++j) { const u32x2 pv = pr[64 * j]; v[j][0] += bflo(pv.x); v[j][1] += bfhi(pv.x); v[j][2] += bflo(pv.y); v[j][3] += bfhi(pv.y); }
;             }
	v_lshlrev_b32_e32 v68, 16, v95
	v_and_b32_e32 v69, 0xffff0000, v95
	v_pk_add_f32 v[44:45], v[44:45], v[68:69]
	s_waitcnt vmcnt(24)
	v_lshlrev_b32_e32 v68, 16, v97
	v_and_b32_e32 v69, 0xffff0000, v97
	v_pk_add_f32 v[44:45], v[44:45], v[68:69]
	s_waitcnt vmcnt(23)
	v_lshlrev_b32_e32 v68, 16, v88
	v_and_b32_e32 v69, 0xffff0000, v88
	v_pk_add_f32 v[42:43], v[42:43], v[68:69]
	s_waitcnt vmcnt(22)
	v_lshlrev_b32_e32 v68, 16, v84
	v_and_b32_e32 v69, 0xffff0000, v84
	v_pk_add_f32 v[42:43], v[42:43], v[68:69]
	s_waitcnt vmcnt(21)
	v_lshlrev_b32_e32 v68, 16, v82
	v_and_b32_e32 v69, 0xffff0000, v82
	v_pk_add_f32 v[42:43], v[42:43], v[68:69]
	s_waitcnt vmcnt(20)
	v_lshlrev_b32_e32 v68, 16, v80
	v_and_b32_e32 v69, 0xffff0000, v80
	v_pk_add_f32 v[42:43], v[42:43], v[68:69]
	s_waitcnt vmcnt(19)
	v_lshlrev_b32_e32 v68, 16, v74
	v_and_b32_e32 v69, 0xffff0000, v74
	v_pk_add_f32 v[42:43], v[42:43], v[68:69]
	s_waitcnt vmcnt(16)
	v_lshlrev_b32_e32 v68, 16, v76
	v_and_b32_e32 v69, 0xffff0000, v76
	v_pk_add_f32 v[42:43], v[42:43], v[68:69]
	s_waitcnt vmcnt(13)
	v_lshlrev_b32_e32 v68, 16, v78
	v_and_b32_e32 v69, 0xffff0000, v78
	v_pk_add_f32 v[42:43], v[42:43], v[68:69]
	s_waitcnt vmcnt(10)
	v_lshlrev_b32_e32 v68, 16, v110
	v_and_b32_e32 v69, 0xffff0000, v110
	v_pk_add_f32 v[42:43], v[42:43], v[68:69]
	v_lshlrev_b32_e32 v68, 16, v89
	v_and_b32_e32 v69, 0xffff0000, v89
	v_pk_add_f32 v[40:41], v[40:41], v[68:69]
	v_lshlrev_b32_e32 v68, 16, v85
	v_and_b32_e32 v69, 0xffff0000, v85
	v_pk_add_f32 v[40:41], v[40:41], v[68:69]
	v_lshlrev_b32_e32 v68, 16, v83
	v_and_b32_e32 v69, 0xffff0000, v83
	v_pk_add_f32 v[40:41], v[40:41], v[68:69]
	v_lshlrev_b32_e32 v68, 16, v81
	v_and_b32_e32 v69, 0xffff0000, v81
	v_pk_add_f32 v[40:41], v[40:41], v[68:69]
	v_lshlrev_b32_e32 v68, 16, v75
	v_and_b32_e32 v69, 0xffff0000, v75
	v_pk_add_f32 v[40:41], v[40:41], v[68:69]
	v_lshlrev_b32_e32 v68, 16, v77
	v_and_b32_e32 v69, 0xffff0000, v77
	v_pk_add_f32 v[40:41], v[40:41], v[68:69]
	v_lshlrev_b32_e32 v68, 16, v79
	v_and_b32_e32 v69, 0xffff0000, v79
	v_pk_add_f32 v[40:41], v[40:41], v[68:69]
	v_lshlrev_b32_e32 v68, 16, v111
	v_and_b32_e32 v69, 0xffff0000, v111
	v_pk_add_f32 v[40:41], v[40:41], v[68:69]
	v_lshlrev_b32_e32 v68, 16, v54
	v_and_b32_e32 v69, 0xffff0000, v54
	v_lshlrev_b32_e32 v54, 16, v55
	v_and_b32_e32 v55, 0xffff0000, v55
	v_pk_add_f32 v[36:37], v[36:37], v[54:55]
	v_lshlrev_b32_e32 v54, 16, v57
	v_and_b32_e32 v55, 0xffff0000, v57
	v_pk_add_f32 v[36:37], v[36:37], v[54:55]
	v_lshlrev_b32_e32 v54, 16, v59
	v_and_b32_e32 v55, 0xffff0000, v59
	v_pk_add_f32 v[36:37], v[36:37], v[54:55]
	s_waitcnt vmcnt(9)
	v_lshlrev_b32_e32 v54, 16, v107
	v_and_b32_e32 v55, 0xffff0000, v107
	v_pk_add_f32 v[36:37], v[36:37], v[54:55]
	s_waitcnt vmcnt(7)
	v_lshlrev_b32_e32 v54, 16, v105
	v_and_b32_e32 v55, 0xffff0000, v105
	v_pk_add_f32 v[36:37], v[36:37], v[54:55]
	s_waitcnt vmcnt(5)
	v_lshlrev_b32_e32 v54, 16, v101
	v_and_b32_e32 v55, 0xffff0000, v101
	v_pk_add_f32 v[36:37], v[36:37], v[54:55]
	s_waitcnt vmcnt(3)
	v_lshlrev_b32_e32 v54, 16, v99
	v_and_b32_e32 v55, 0xffff0000, v99
	v_pk_add_f32 v[36:37], v[36:37], v[54:55]
	s_waitcnt vmcnt(1)
; __device__ __forceinline__ unsigned pk2(float lo, float hi) { const f32x2_t v = {lo, hi}; const bf16v2_t b = __builtin_convertvector(v, bf16v2_t); return __builtin_bit_cast(unsigned, b); }
; __device__ __forceinline__ float bflo(unsigned u) { return __uint_as_float(u << 16); }
; __device__ __forceinline__ float bfhi(unsigned u) { return __uint_as_float(u & 0xffff0000u); }
; __device__ __forceinline__ void norm_phase(const Args& A, Frame& F, int l, int s, bool latonly, bool tailsum) {
;     ...
;         if (tailsum && row >= 16384) {
; #pragma unroll
;             for (int sp = 0; sp < 8; ++sp) {
;                 const u32x2* pr = (const u32x2*)(WSB(WS_PART) + ((size_t)sp * 2048 + (row - 16384)) * D) + F.lane;
; #pragma unroll
;                 for (int j = 0; j < 4; ++j) { const u32x2 pv = pr[64 * j]; v[j][0] += bflo(pv.x); v[j][1] += bfhi(pv.x); v[j][2] += bflo(pv.y); v[j][3] += bfhi(pv.y); }
;             }
;             u32x2* xw = (u32x2*)(WSB(WS_R) + (size_t)row * D) + F.lane;
; #pragma unroll
;             for (int j = 0; j < 4; ++j) { u32x2 o; o.x = pk2(v[j][0], v[j][1]); o.y = pk2(v[j][2], v[j][3]); xw[64 * j] = o; v[j][0] = bflo(o.x); v[j][1] = bfhi(o.x); v[j][2] = bflo(o.y); v[j][3] = bfhi(o.y); }
;         }
; #pragma unroll
;         for (int j = 0; j < 4; ++j) ss += (v[j][0] * v[j][0] + v[j][1] * v[j][1]) + (v[j][2] * v[j][2] + v[j][3] * v[j][3]);
	v_lshlrev_b32_e32 v54, 16, v115
	v_and_b32_e32 v55, 0xffff0000, v115
	v_pk_add_f32 v[36:37], v[36:37], v[54:55]
	v_lshlrev_b32_e32 v54, 16, v52
	v_and_b32_e32 v55, 0xffff0000, v52
	v_lshlrev_b32_e32 v52, 16, v53
	v_and_b32_e32 v53, 0xffff0000, v53
	v_pk_add_f32 v[34:35], v[34:35], v[54:55]
	v_lshlrev_b32_e32 v54, 16, v50
	v_and_b32_e32 v55, 0xffff0000, v50
	v_pk_add_f32 v[32:33], v[32:33], v[52:53]
	v_lshlrev_b32_e32 v50, 16, v51
	v_and_b32_e32 v51, 0xffff0000, v51
	v_and_b32_e32 v117, 0xffff0000, v86
	v_pk_add_f32 v[38:39], v[38:39], v[68:69]
	v_lshlrev_b32_e32 v68, 16, v56
	v_and_b32_e32 v69, 0xffff0000, v56
	v_pk_add_f32 v[34:35], v[34:35], v[54:55]
	v_lshlrev_b32_e32 v54, 16, v48
	v_and_b32_e32 v55, 0xffff0000, v48
	v_pk_add_f32 v[32:33], v[32:33], v[50:51]
	v_lshlrev_b32_e32 v48, 16, v49
	v_and_b32_e32 v49, 0xffff0000, v49
	v_pk_add_f32 v[46:47], v[46:47], v[116:117]
	v_lshlrev_b32_e32 v116, 16, v90
	v_and_b32_e32 v117, 0xffff0000, v90
	v_pk_add_f32 v[38:39], v[38:39], v[68:69]
	v_lshlrev_b32_e32 v68, 16, v58
	v_and_b32_e32 v69, 0xffff0000, v58
	v_pk_add_f32 v[32:33], v[32:33], v[48:49]
	v_lshlrev_b32_e32 v48, 16, v67
	v_and_b32_e32 v49, 0xffff0000, v67
	v_pk_add_f32 v[46:47], v[46:47], v[116:117]
	v_lshlrev_b32_e32 v116, 16, v92
	v_and_b32_e32 v117, 0xffff0000, v92
	v_pk_add_f32 v[38:39], v[38:39], v[68:69]
	v_lshlrev_b32_e32 v68, 16, v106
	v_and_b32_e32 v69, 0xffff0000, v106
	v_pk_add_f32 v[32:33], v[32:33], v[48:49]
	v_lshlrev_b32_e32 v48, 16, v65
	v_and_b32_e32 v49, 0xffff0000, v65
	v_pk_add_f32 v[46:47], v[46:47], v[116:117]
	v_lshlrev_b32_e32 v116, 16, v94
	v_and_b32_e32 v117, 0xffff0000, v94
	v_pk_add_f32 v[38:39], v[38:39], v[68:69]
	v_lshlrev_b32_e32 v68, 16, v104
	v_and_b32_e32 v69, 0xffff0000, v104
	v_pk_add_f32 v[34:35], v[34:35], v[54:55]
	v_lshlrev_b32_e32 v54, 16, v66
	v_and_b32_e32 v55, 0xffff0000, v66
	v_pk_add_f32 v[32:33], v[32:33], v[48:49]
	v_lshlrev_b32_e32 v48, 16, v63
	v_and_b32_e32 v49, 0xffff0000, v63
	v_pk_add_f32 v[46:47], v[46:47], v[116:117]
	v_lshlrev_b32_e32 v116, 16, v96
	v_and_b32_e32 v117, 0xffff0000, v96
	v_pk_add_f32 v[38:39], v[38:39], v[68:69]
	v_lshlrev_b32_e32 v68, 16, v100
	v_and_b32_e32 v69, 0xffff0000, v100
	v_pk_add_f32 v[34:35], v[34:35], v[54:55]
	v_lshlrev_b32_e32 v54, 16, v64
	v_and_b32_e32 v55, 0xffff0000, v64
	v_pk_add_f32 v[32:33], v[32:33], v[48:49]
	v_lshlrev_b32_e32 v48, 16, v61
	v_and_b32_e32 v49, 0xffff0000, v61
	v_pk_add_f32 v[46:47], v[46:47], v[116:117]
	v_pk_add_f32 v[38:39], v[38:39], v[68:69]
	v_lshlrev_b32_e32 v68, 16, v98
	v_and_b32_e32 v69, 0xffff0000, v98
	v_pk_add_f32 v[34:35], v[34:35], v[54:55]
	v_lshlrev_b32_e32 v54, 16, v62
	v_and_b32_e32 v55, 0xffff0000, v62
	v_pk_add_f32 v[32:33], v[32:33], v[48:49]
	s_waitcnt vmcnt(0)
	v_lshlrev_b32_e32 v48, 16, v109
	v_and_b32_e32 v49, 0xffff0000, v109
	v_pk_add_f32 v[38:39], v[38:39], v[68:69]
	v_lshlrev_b32_e32 v68, 16, v114
	v_and_b32_e32 v69, 0xffff0000, v114
	v_pk_add_f32 v[34:35], v[34:35], v[54:55]
	v_lshlrev_b32_e32 v54, 16, v60
	v_and_b32_e32 v55, 0xffff0000, v60
	v_pk_add_f32 v[32:33], v[32:33], v[48:49]
	v_lshl_add_u64 v[48:49], v[18:19], 0, s[42:43]
	v_cvt_pk_bf16_f32 v50, v46, v47
	v_cvt_pk_bf16_f32 v51, v44, v45
	v_pk_add_f32 v[38:39], v[38:39], v[68:69]
	v_pk_add_f32 v[34:35], v[34:35], v[54:55]
	v_lshlrev_b32_e32 v54, 16, v108
	v_and_b32_e32 v55, 0xffff0000, v108
	global_store_dwordx2 v[48:49], v[50:51], off
	v_lshlrev_b32_e32 v46, 16, v50
	v_and_b32_e32 v47, 0xffff0000, v50
	v_lshlrev_b32_e32 v44, 16, v51
	v_and_b32_e32 v45, 0xffff0000, v51
	v_cvt_pk_bf16_f32 v50, v42, v43
	v_cvt_pk_bf16_f32 v51, v40, v41
	v_pk_add_f32 v[34:35], v[34:35], v[54:55]
	global_store_dwordx2 v[48:49], v[50:51], off offset:512
	v_lshlrev_b32_e32 v42, 16, v50
	v_and_b32_e32 v43, 0xffff0000, v50
	v_lshlrev_b32_e32 v40, 16, v51
	v_and_b32_e32 v41, 0xffff0000, v51
	v_cvt_pk_bf16_f32 v50, v38, v39
	v_cvt_pk_bf16_f32 v51, v36, v37
	global_store_dwordx2 v[48:49], v[50:51], off offset:1024
	v_lshlrev_b32_e32 v38, 16, v50
	v_and_b32_e32 v39, 0xffff0000, v50
	v_lshlrev_b32_e32 v36, 16, v51
	v_and_b32_e32 v37, 0xffff0000, v51
	v_cvt_pk_bf16_f32 v50, v34, v35
	v_cvt_pk_bf16_f32 v51, v32, v33
	v_lshlrev_b32_e32 v34, 16, v50
	v_and_b32_e32 v35, 0xffff0000, v50
	v_lshlrev_b32_e32 v32, 16, v51
	v_and_b32_e32 v33, 0xffff0000, v51
	global_store_dwordx2 v[48:49], v[50:51], off offset:1536
	s_branch .LBB0_693
